# workgroup-local single-pass int8 weight conversion (16-column blocks), SDWA byte packing
# baseline (speedup 1.0000x reference)
.Lc16_gates_nocm:
	v_div_scale_f32 v175, s[70:71], v220, v220, s74
	v_rcp_f32_e32 v176, v175
	s_nop 0
	v_fma_f32 v177, -v175, v176, 1.0
	v_fmac_f32_e32 v176, v177, v176
	v_div_scale_f32 v177, vcc, s74, v220, s74
	v_mul_f32_e32 v178, v177, v176
	v_fma_f32 v180, -v175, v178, v177
	v_fmac_f32_e32 v178, v180, v176
	v_fma_f32 v175, -v175, v178, v177
	s_nop 0
	v_div_fmas_f32 v175, v175, v176, v178
	v_div_fixup_f32 v175, v175, v220, s74
	v_cmp_lt_f32_e32 vcc, 0, v220
	s_nop 1
	v_cndmask_b32_e32 v226, 0, v175, vcc
	v_div_scale_f32 v175, s[70:71], v221, v221, s74
	v_rcp_f32_e32 v176, v175
	s_nop 0
	v_fma_f32 v177, -v175, v176, 1.0
	v_fmac_f32_e32 v176, v177, v176
	v_div_scale_f32 v177, vcc, s74, v221, s74
	v_mul_f32_e32 v178, v177, v176
	v_fma_f32 v180, -v175, v178, v177
	v_fmac_f32_e32 v178, v180, v176
	v_fma_f32 v175, -v175, v178, v177
	s_nop 0
	v_div_fmas_f32 v175, v175, v176, v178
	v_div_fixup_f32 v175, v175, v221, s74
	v_cmp_lt_f32_e32 vcc, 0, v221
	s_nop 1
	v_cndmask_b32_e32 v227, 0, v175, vcc
	v_div_scale_f32 v175, s[70:71], v222, v222, s74
	v_rcp_f32_e32 v176, v175
	s_nop 0
	v_fma_f32 v177, -v175, v176, 1.0
	v_fmac_f32_e32 v176, v177, v176
	v_div_scale_f32 v177, vcc, s74, v222, s74
	v_mul_f32_e32 v178, v177, v176
	v_fma_f32 v180, -v175, v178, v177
	v_fmac_f32_e32 v178, v180, v176
	v_fma_f32 v175, -v175, v178, v177
	s_nop 0
	v_div_fmas_f32 v175, v175, v176, v178
	v_div_fixup_f32 v175, v175, v222, s74
	v_cmp_lt_f32_e32 vcc, 0, v222
	s_nop 1
	v_cndmask_b32_e32 v228, 0, v175, vcc
	v_div_scale_f32 v175, s[70:71], v223, v223, s74
	v_rcp_f32_e32 v176, v175
	s_nop 0
	v_fma_f32 v177, -v175, v176, 1.0
	v_fmac_f32_e32 v176, v177, v176
	v_div_scale_f32 v177, vcc, s74, v223, s74
	v_mul_f32_e32 v178, v177, v176
	v_fma_f32 v180, -v175, v178, v177
	v_fmac_f32_e32 v178, v180, v176
	v_fma_f32 v175, -v175, v178, v177
	s_nop 0
	v_div_fmas_f32 v175, v175, v176, v178
	v_div_fixup_f32 v175, v175, v223, s74
	v_cmp_lt_f32_e32 vcc, 0, v223
	s_nop 1
	v_cndmask_b32_e32 v229, 0, v175, vcc
	s_add_u32 s10, s0, s33
	s_lshl_b32 s3, s10, 6
	s_add_u32 s56, s48, s3
	s_addc_u32 s57, s49, 0
	v_mul_f32_e32 v186, v6, v226
	v_mul_f32_e32 v187, v7, v227
	v_rndne_f32_e32 v186, v186
	v_rndne_f32_e32 v187, v187
	v_cvt_i32_f32_sdwa v190, v186 dst_sel:BYTE_0 dst_unused:UNUSED_PAD src0_sel:DWORD
	v_cvt_i32_f32_sdwa v196, v187 dst_sel:BYTE_0 dst_unused:UNUSED_PAD src0_sel:DWORD
	v_mul_f32_e32 v186, v10, v226
	v_mul_f32_e32 v187, v11, v227
	v_rndne_f32_e32 v186, v186
	v_rndne_f32_e32 v187, v187
	v_cvt_i32_f32_sdwa v190, v186 dst_sel:BYTE_1 dst_unused:UNUSED_PRESERVE src0_sel:DWORD
	v_cvt_i32_f32_sdwa v196, v187 dst_sel:BYTE_1 dst_unused:UNUSED_PRESERVE src0_sel:DWORD
	v_mul_f32_e32 v186, v14, v226
	v_mul_f32_e32 v187, v15, v227
	v_rndne_f32_e32 v186, v186
	v_rndne_f32_e32 v187, v187
	v_cvt_i32_f32_sdwa v190, v186 dst_sel:BYTE_2 dst_unused:UNUSED_PRESERVE src0_sel:DWORD
	v_cvt_i32_f32_sdwa v196, v187 dst_sel:BYTE_2 dst_unused:UNUSED_PRESERVE src0_sel:DWORD
	v_mul_f32_e32 v186, v18, v226
	v_mul_f32_e32 v187, v19, v227
	v_rndne_f32_e32 v186, v186
	v_rndne_f32_e32 v187, v187
	v_cvt_i32_f32_sdwa v190, v186 dst_sel:BYTE_3 dst_unused:UNUSED_PRESERVE src0_sel:DWORD
	v_cvt_i32_f32_sdwa v196, v187 dst_sel:BYTE_3 dst_unused:UNUSED_PRESERVE src0_sel:DWORD
	s_nop 0
	ds_write_b32 v139, v190 offset:0
	ds_write_b32 v139, v196 offset:512
	v_mul_f32_e32 v186, v8, v228
	v_mul_f32_e32 v187, v9, v229
	v_rndne_f32_e32 v186, v186
	v_rndne_f32_e32 v187, v187
	v_cvt_i32_f32_sdwa v190, v186 dst_sel:BYTE_0 dst_unused:UNUSED_PAD src0_sel:DWORD
	v_cvt_i32_f32_sdwa v196, v187 dst_sel:BYTE_0 dst_unused:UNUSED_PAD src0_sel:DWORD
	v_mul_f32_e32 v186, v12, v228
	v_mul_f32_e32 v187, v13, v229
	v_rndne_f32_e32 v186, v186
	v_rndne_f32_e32 v187, v187
	v_cvt_i32_f32_sdwa v190, v186 dst_sel:BYTE_1 dst_unused:UNUSED_PRESERVE src0_sel:DWORD
	v_cvt_i32_f32_sdwa v196, v187 dst_sel:BYTE_1 dst_unused:UNUSED_PRESERVE src0_sel:DWORD
	v_mul_f32_e32 v186, v16, v228
	v_mul_f32_e32 v187, v17, v229
	v_rndne_f32_e32 v186, v186
	v_rndne_f32_e32 v187, v187
	v_cvt_i32_f32_sdwa v190, v186 dst_sel:BYTE_2 dst_unused:UNUSED_PRESERVE src0_sel:DWORD
	v_cvt_i32_f32_sdwa v196, v187 dst_sel:BYTE_2 dst_unused:UNUSED_PRESERVE src0_sel:DWORD
	v_mul_f32_e32 v186, v20, v228
	v_mul_f32_e32 v187, v21, v229
	v_rndne_f32_e32 v186, v186
	v_rndne_f32_e32 v187, v187
	v_cvt_i32_f32_sdwa v190, v186 dst_sel:BYTE_3 dst_unused:UNUSED_PRESERVE src0_sel:DWORD
	v_cvt_i32_f32_sdwa v196, v187 dst_sel:BYTE_3 dst_unused:UNUSED_PRESERVE src0_sel:DWORD
	s_nop 0
	ds_write_b32 v139, v190 offset:1024
	ds_write_b32 v139, v196 offset:1536
	s_cmp_ge_u32 s10, 0x200
	s_cbranch_scc1 .Lc16_gates_nopf_0
	global_load_dwordx4 v[6:9], v138, s[56:57]
	s_add_u32 s56, s56, 0x8000
	s_addc_u32 s57, s57, 0
	global_load_dwordx4 v[10:13], v138, s[56:57]
	s_add_u32 s56, s56, 0x8000
	s_addc_u32 s57, s57, 0
	global_load_dwordx4 v[14:17], v138, s[56:57]
	s_add_u32 s56, s56, 0x8000
	s_addc_u32 s57, s57, 0
	global_load_dwordx4 v[18:21], v138, s[56:57]
	s_add_u32 s56, s56, 0x1e8000
	s_addc_u32 s57, s57, 0
.Lc16_gates_nopf_0:
	v_mul_f32_e32 v186, v22, v226
	v_mul_f32_e32 v187, v23, v227
	v_rndne_f32_e32 v186, v186
	v_rndne_f32_e32 v187, v187
	v_cvt_i32_f32_sdwa v190, v186 dst_sel:BYTE_0 dst_unused:UNUSED_PAD src0_sel:DWORD
	v_cvt_i32_f32_sdwa v196, v187 dst_sel:BYTE_0 dst_unused:UNUSED_PAD src0_sel:DWORD
	v_mul_f32_e32 v186, v26, v226
	v_mul_f32_e32 v187, v27, v227
	v_rndne_f32_e32 v186, v186
	v_rndne_f32_e32 v187, v187
	v_cvt_i32_f32_sdwa v190, v186 dst_sel:BYTE_1 dst_unused:UNUSED_PRESERVE src0_sel:DWORD
	v_cvt_i32_f32_sdwa v196, v187 dst_sel:BYTE_1 dst_unused:UNUSED_PRESERVE src0_sel:DWORD
	v_mul_f32_e32 v186, v30, v226
	v_mul_f32_e32 v187, v31, v227
	v_rndne_f32_e32 v186, v186
	v_rndne_f32_e32 v187, v187
	v_cvt_i32_f32_sdwa v190, v186 dst_sel:BYTE_2 dst_unused:UNUSED_PRESERVE src0_sel:DWORD
	v_cvt_i32_f32_sdwa v196, v187 dst_sel:BYTE_2 dst_unused:UNUSED_PRESERVE src0_sel:DWORD
	v_mul_f32_e32 v186, v34, v226
	v_mul_f32_e32 v187, v35, v227
	v_rndne_f32_e32 v186, v186
	v_rndne_f32_e32 v187, v187
	v_cvt_i32_f32_sdwa v190, v186 dst_sel:BYTE_3 dst_unused:UNUSED_PRESERVE src0_sel:DWORD
	v_cvt_i32_f32_sdwa v196, v187 dst_sel:BYTE_3 dst_unused:UNUSED_PRESERVE src0_sel:DWORD
	s_nop 0
	ds_write_b32 v139, v190 offset:64
	ds_write_b32 v139, v196 offset:576
	v_mul_f32_e32 v186, v24, v228
	v_mul_f32_e32 v187, v25, v229
	v_rndne_f32_e32 v186, v186
	v_rndne_f32_e32 v187, v187
	v_cvt_i32_f32_sdwa v190, v186 dst_sel:BYTE_0 dst_unused:UNUSED_PAD src0_sel:DWORD
	v_cvt_i32_f32_sdwa v196, v187 dst_sel:BYTE_0 dst_unused:UNUSED_PAD src0_sel:DWORD
	v_mul_f32_e32 v186, v28, v228
	v_mul_f32_e32 v187, v29, v229
	v_rndne_f32_e32 v186, v186
	v_rndne_f32_e32 v187, v187
	v_cvt_i32_f32_sdwa v190, v186 dst_sel:BYTE_1 dst_unused:UNUSED_PRESERVE src0_sel:DWORD
	v_cvt_i32_f32_sdwa v196, v187 dst_sel:BYTE_1 dst_unused:UNUSED_PRESERVE src0_sel:DWORD
	v_mul_f32_e32 v186, v32, v228
	v_mul_f32_e32 v187, v33, v229
	v_rndne_f32_e32 v186, v186
	v_rndne_f32_e32 v187, v187
	v_cvt_i32_f32_sdwa v190, v186 dst_sel:BYTE_2 dst_unused:UNUSED_PRESERVE src0_sel:DWORD
	v_cvt_i32_f32_sdwa v196, v187 dst_sel:BYTE_2 dst_unused:UNUSED_PRESERVE src0_sel:DWORD
	v_mul_f32_e32 v186, v36, v228
	v_mul_f32_e32 v187, v37, v229
	v_rndne_f32_e32 v186, v186
	v_rndne_f32_e32 v187, v187
	v_cvt_i32_f32_sdwa v190, v186 dst_sel:BYTE_3 dst_unused:UNUSED_PRESERVE src0_sel:DWORD
	v_cvt_i32_f32_sdwa v196, v187 dst_sel:BYTE_3 dst_unused:UNUSED_PRESERVE src0_sel:DWORD
	s_nop 0
	ds_write_b32 v139, v190 offset:1088
	ds_write_b32 v139, v196 offset:1600
	s_cmp_ge_u32 s10, 0x200
	s_cbranch_scc1 .Lc16_gates_nopf_1
	global_load_dwordx4 v[22:25], v138, s[56:57]
	s_add_u32 s56, s56, 0x8000
	s_addc_u32 s57, s57, 0
	global_load_dwordx4 v[26:29], v138, s[56:57]
	s_add_u32 s56, s56, 0x8000
	s_addc_u32 s57, s57, 0
	global_load_dwordx4 v[30:33], v138, s[56:57]
	s_add_u32 s56, s56, 0x8000
	s_addc_u32 s57, s57, 0
	global_load_dwordx4 v[34:37], v138, s[56:57]
	s_add_u32 s56, s56, 0x1e8000
	s_addc_u32 s57, s57, 0
.Lc16_gates_nopf_1:
	v_mul_f32_e32 v186, v38, v226
	v_mul_f32_e32 v187, v39, v227
	v_rndne_f32_e32 v186, v186
	v_rndne_f32_e32 v187, v187
	v_cvt_i32_f32_sdwa v190, v186 dst_sel:BYTE_0 dst_unused:UNUSED_PAD src0_sel:DWORD
	v_cvt_i32_f32_sdwa v196, v187 dst_sel:BYTE_0 dst_unused:UNUSED_PAD src0_sel:DWORD
	v_mul_f32_e32 v186, v42, v226
	v_mul_f32_e32 v187, v43, v227
	v_rndne_f32_e32 v186, v186
	v_rndne_f32_e32 v187, v187
	v_cvt_i32_f32_sdwa v190, v186 dst_sel:BYTE_1 dst_unused:UNUSED_PRESERVE src0_sel:DWORD
	v_cvt_i32_f32_sdwa v196, v187 dst_sel:BYTE_1 dst_unused:UNUSED_PRESERVE src0_sel:DWORD
	v_mul_f32_e32 v186, v46, v226
	v_mul_f32_e32 v187, v47, v227
	v_rndne_f32_e32 v186, v186
	v_rndne_f32_e32 v187, v187
	v_cvt_i32_f32_sdwa v190, v186 dst_sel:BYTE_2 dst_unused:UNUSED_PRESERVE src0_sel:DWORD
	v_cvt_i32_f32_sdwa v196, v187 dst_sel:BYTE_2 dst_unused:UNUSED_PRESERVE src0_sel:DWORD
	v_mul_f32_e32 v186, v50, v226
	v_mul_f32_e32 v187, v51, v227
	v_rndne_f32_e32 v186, v186
	v_rndne_f32_e32 v187, v187
	v_cvt_i32_f32_sdwa v190, v186 dst_sel:BYTE_3 dst_unused:UNUSED_PRESERVE src0_sel:DWORD
	v_cvt_i32_f32_sdwa v196, v187 dst_sel:BYTE_3 dst_unused:UNUSED_PRESERVE src0_sel:DWORD
	s_nop 0
	ds_write_b32 v139, v190 offset:128
	ds_write_b32 v139, v196 offset:640
	v_mul_f32_e32 v186, v40, v228
	v_mul_f32_e32 v187, v41, v229
	v_rndne_f32_e32 v186, v186
	v_rndne_f32_e32 v187, v187
	v_cvt_i32_f32_sdwa v190, v186 dst_sel:BYTE_0 dst_unused:UNUSED_PAD src0_sel:DWORD
	v_cvt_i32_f32_sdwa v196, v187 dst_sel:BYTE_0 dst_unused:UNUSED_PAD src0_sel:DWORD
	v_mul_f32_e32 v186, v44, v228
	v_mul_f32_e32 v187, v45, v229
	v_rndne_f32_e32 v186, v186
	v_rndne_f32_e32 v187, v187
	v_cvt_i32_f32_sdwa v190, v186 dst_sel:BYTE_1 dst_unused:UNUSED_PRESERVE src0_sel:DWORD
	v_cvt_i32_f32_sdwa v196, v187 dst_sel:BYTE_1 dst_unused:UNUSED_PRESERVE src0_sel:DWORD
	v_mul_f32_e32 v186, v48, v228
	v_mul_f32_e32 v187, v49, v229
	v_rndne_f32_e32 v186, v186
	v_rndne_f32_e32 v187, v187
	v_cvt_i32_f32_sdwa v190, v186 dst_sel:BYTE_2 dst_unused:UNUSED_PRESERVE src0_sel:DWORD
	v_cvt_i32_f32_sdwa v196, v187 dst_sel:BYTE_2 dst_unused:UNUSED_PRESERVE src0_sel:DWORD
	v_mul_f32_e32 v186, v52, v228
	v_mul_f32_e32 v187, v53, v229
	v_rndne_f32_e32 v186, v186
	v_rndne_f32_e32 v187, v187
	v_cvt_i32_f32_sdwa v190, v186 dst_sel:BYTE_3 dst_unused:UNUSED_PRESERVE src0_sel:DWORD
	v_cvt_i32_f32_sdwa v196, v187 dst_sel:BYTE_3 dst_unused:UNUSED_PRESERVE src0_sel:DWORD
	s_nop 0
	ds_write_b32 v139, v190 offset:1152
	ds_write_b32 v139, v196 offset:1664
	s_cmp_ge_u32 s10, 0x200
	s_cbranch_scc1 .Lc16_gates_nopf_2
	global_load_dwordx4 v[38:41], v138, s[56:57]
	s_add_u32 s56, s56, 0x8000
	s_addc_u32 s57, s57, 0
	global_load_dwordx4 v[42:45], v138, s[56:57]
	s_add_u32 s56, s56, 0x8000
	s_addc_u32 s57, s57, 0
	global_load_dwordx4 v[46:49], v138, s[56:57]
	s_add_u32 s56, s56, 0x8000
	s_addc_u32 s57, s57, 0
	global_load_dwordx4 v[50:53], v138, s[56:57]
	s_add_u32 s56, s56, 0x1e8000
	s_addc_u32 s57, s57, 0
.Lc16_gates_nopf_2:
	v_mul_f32_e32 v186, v54, v226
	v_mul_f32_e32 v187, v55, v227
	v_rndne_f32_e32 v186, v186
	v_rndne_f32_e32 v187, v187
	v_cvt_i32_f32_sdwa v190, v186 dst_sel:BYTE_0 dst_unused:UNUSED_PAD src0_sel:DWORD
	v_cvt_i32_f32_sdwa v196, v187 dst_sel:BYTE_0 dst_unused:UNUSED_PAD src0_sel:DWORD
	v_mul_f32_e32 v186, v58, v226
	v_mul_f32_e32 v187, v59, v227
	v_rndne_f32_e32 v186, v186
	v_rndne_f32_e32 v187, v187
	v_cvt_i32_f32_sdwa v190, v186 dst_sel:BYTE_1 dst_unused:UNUSED_PRESERVE src0_sel:DWORD
	v_cvt_i32_f32_sdwa v196, v187 dst_sel:BYTE_1 dst_unused:UNUSED_PRESERVE src0_sel:DWORD
	v_mul_f32_e32 v186, v62, v226
	v_mul_f32_e32 v187, v63, v227
	v_rndne_f32_e32 v186, v186
	v_rndne_f32_e32 v187, v187
	v_cvt_i32_f32_sdwa v190, v186 dst_sel:BYTE_2 dst_unused:UNUSED_PRESERVE src0_sel:DWORD
	v_cvt_i32_f32_sdwa v196, v187 dst_sel:BYTE_2 dst_unused:UNUSED_PRESERVE src0_sel:DWORD
	v_mul_f32_e32 v186, v66, v226
	v_mul_f32_e32 v187, v67, v227
	v_rndne_f32_e32 v186, v186
	v_rndne_f32_e32 v187, v187
	v_cvt_i32_f32_sdwa v190, v186 dst_sel:BYTE_3 dst_unused:UNUSED_PRESERVE src0_sel:DWORD
	v_cvt_i32_f32_sdwa v196, v187 dst_sel:BYTE_3 dst_unused:UNUSED_PRESERVE src0_sel:DWORD
	s_nop 0
	ds_write_b32 v139, v190 offset:192
	ds_write_b32 v139, v196 offset:704
	v_mul_f32_e32 v186, v56, v228
	v_mul_f32_e32 v187, v57, v229
	v_rndne_f32_e32 v186, v186
	v_rndne_f32_e32 v187, v187
	v_cvt_i32_f32_sdwa v190, v186 dst_sel:BYTE_0 dst_unused:UNUSED_PAD src0_sel:DWORD
	v_cvt_i32_f32_sdwa v196, v187 dst_sel:BYTE_0 dst_unused:UNUSED_PAD src0_sel:DWORD
	v_mul_f32_e32 v186, v60, v228
	v_mul_f32_e32 v187, v61, v229
	v_rndne_f32_e32 v186, v186
	v_rndne_f32_e32 v187, v187
	v_cvt_i32_f32_sdwa v190, v186 dst_sel:BYTE_1 dst_unused:UNUSED_PRESERVE src0_sel:DWORD
	v_cvt_i32_f32_sdwa v196, v187 dst_sel:BYTE_1 dst_unused:UNUSED_PRESERVE src0_sel:DWORD
	v_mul_f32_e32 v186, v64, v228
	v_mul_f32_e32 v187, v65, v229
	v_rndne_f32_e32 v186, v186
	v_rndne_f32_e32 v187, v187
	v_cvt_i32_f32_sdwa v190, v186 dst_sel:BYTE_2 dst_unused:UNUSED_PRESERVE src0_sel:DWORD
	v_cvt_i32_f32_sdwa v196, v187 dst_sel:BYTE_2 dst_unused:UNUSED_PRESERVE src0_sel:DWORD
	v_mul_f32_e32 v186, v68, v228
	v_mul_f32_e32 v187, v69, v229
	v_rndne_f32_e32 v186, v186
	v_rndne_f32_e32 v187, v187
	v_cvt_i32_f32_sdwa v190, v186 dst_sel:BYTE_3 dst_unused:UNUSED_PRESERVE src0_sel:DWORD
	v_cvt_i32_f32_sdwa v196, v187 dst_sel:BYTE_3 dst_unused:UNUSED_PRESERVE src0_sel:DWORD
	s_nop 0
	ds_write_b32 v139, v190 offset:1216
	ds_write_b32 v139, v196 offset:1728
	s_cmp_ge_u32 s10, 0x200
	s_cbranch_scc1 .Lc16_gates_nopf_3
	global_load_dwordx4 v[54:57], v138, s[56:57]
	s_add_u32 s56, s56, 0x8000
	s_addc_u32 s57, s57, 0
	global_load_dwordx4 v[58:61], v138, s[56:57]
	s_add_u32 s56, s56, 0x8000
	s_addc_u32 s57, s57, 0
	global_load_dwordx4 v[62:65], v138, s[56:57]
	s_add_u32 s56, s56, 0x8000
	s_addc_u32 s57, s57, 0
	global_load_dwordx4 v[66:69], v138, s[56:57]
	s_add_u32 s56, s56, 0x1e8000
	s_addc_u32 s57, s57, 0
.Lc16_gates_nopf_3:
	v_mul_f32_e32 v186, v70, v226
	v_mul_f32_e32 v187, v71, v227
	v_rndne_f32_e32 v186, v186
	v_rndne_f32_e32 v187, v187
	v_cvt_i32_f32_sdwa v190, v186 dst_sel:BYTE_0 dst_unused:UNUSED_PAD src0_sel:DWORD
	v_cvt_i32_f32_sdwa v196, v187 dst_sel:BYTE_0 dst_unused:UNUSED_PAD src0_sel:DWORD
	v_mul_f32_e32 v186, v74, v226
	v_mul_f32_e32 v187, v75, v227
	v_rndne_f32_e32 v186, v186
	v_rndne_f32_e32 v187, v187
	v_cvt_i32_f32_sdwa v190, v186 dst_sel:BYTE_1 dst_unused:UNUSED_PRESERVE src0_sel:DWORD
	v_cvt_i32_f32_sdwa v196, v187 dst_sel:BYTE_1 dst_unused:UNUSED_PRESERVE src0_sel:DWORD
	v_mul_f32_e32 v186, v78, v226
	v_mul_f32_e32 v187, v79, v227
	v_rndne_f32_e32 v186, v186
	v_rndne_f32_e32 v187, v187
	v_cvt_i32_f32_sdwa v190, v186 dst_sel:BYTE_2 dst_unused:UNUSED_PRESERVE src0_sel:DWORD
	v_cvt_i32_f32_sdwa v196, v187 dst_sel:BYTE_2 dst_unused:UNUSED_PRESERVE src0_sel:DWORD
	v_mul_f32_e32 v186, v82, v226
	v_mul_f32_e32 v187, v83, v227
	v_rndne_f32_e32 v186, v186
	v_rndne_f32_e32 v187, v187
	v_cvt_i32_f32_sdwa v190, v186 dst_sel:BYTE_3 dst_unused:UNUSED_PRESERVE src0_sel:DWORD
	v_cvt_i32_f32_sdwa v196, v187 dst_sel:BYTE_3 dst_unused:UNUSED_PRESERVE src0_sel:DWORD
	s_nop 0
	ds_write_b32 v139, v190 offset:256
	ds_write_b32 v139, v196 offset:768
	v_mul_f32_e32 v186, v72, v228
	v_mul_f32_e32 v187, v73, v229
	v_rndne_f32_e32 v186, v186
	v_rndne_f32_e32 v187, v187
	v_cvt_i32_f32_sdwa v190, v186 dst_sel:BYTE_0 dst_unused:UNUSED_PAD src0_sel:DWORD
	v_cvt_i32_f32_sdwa v196, v187 dst_sel:BYTE_0 dst_unused:UNUSED_PAD src0_sel:DWORD
	v_mul_f32_e32 v186, v76, v228
	v_mul_f32_e32 v187, v77, v229
	v_rndne_f32_e32 v186, v186
	v_rndne_f32_e32 v187, v187
	v_cvt_i32_f32_sdwa v190, v186 dst_sel:BYTE_1 dst_unused:UNUSED_PRESERVE src0_sel:DWORD
	v_cvt_i32_f32_sdwa v196, v187 dst_sel:BYTE_1 dst_unused:UNUSED_PRESERVE src0_sel:DWORD
	v_mul_f32_e32 v186, v80, v228
	v_mul_f32_e32 v187, v81, v229
	v_rndne_f32_e32 v186, v186
	v_rndne_f32_e32 v187, v187
	v_cvt_i32_f32_sdwa v190, v186 dst_sel:BYTE_2 dst_unused:UNUSED_PRESERVE src0_sel:DWORD
	v_cvt_i32_f32_sdwa v196, v187 dst_sel:BYTE_2 dst_unused:UNUSED_PRESERVE src0_sel:DWORD
	v_mul_f32_e32 v186, v84, v228
	v_mul_f32_e32 v187, v85, v229
	v_rndne_f32_e32 v186, v186
	v_rndne_f32_e32 v187, v187
	v_cvt_i32_f32_sdwa v190, v186 dst_sel:BYTE_3 dst_unused:UNUSED_PRESERVE src0_sel:DWORD
	v_cvt_i32_f32_sdwa v196, v187 dst_sel:BYTE_3 dst_unused:UNUSED_PRESERVE src0_sel:DWORD
	s_nop 0
	ds_write_b32 v139, v190 offset:1280
	ds_write_b32 v139, v196 offset:1792
	s_cmp_ge_u32 s10, 0x200
	s_cbranch_scc1 .Lc16_gates_nopf_4
	global_load_dwordx4 v[70:73], v138, s[56:57]
	s_add_u32 s56, s56, 0x8000
	s_addc_u32 s57, s57, 0
	global_load_dwordx4 v[74:77], v138, s[56:57]
	s_add_u32 s56, s56, 0x8000
	s_addc_u32 s57, s57, 0
	global_load_dwordx4 v[78:81], v138, s[56:57]
	s_add_u32 s56, s56, 0x8000
	s_addc_u32 s57, s57, 0
	global_load_dwordx4 v[82:85], v138, s[56:57]
	s_add_u32 s56, s56, 0x1e8000
	s_addc_u32 s57, s57, 0
.Lc16_gates_nopf_4:
	v_mul_f32_e32 v186, v86, v226
	v_mul_f32_e32 v187, v87, v227
	v_rndne_f32_e32 v186, v186
	v_rndne_f32_e32 v187, v187
	v_cvt_i32_f32_sdwa v190, v186 dst_sel:BYTE_0 dst_unused:UNUSED_PAD src0_sel:DWORD
	v_cvt_i32_f32_sdwa v196, v187 dst_sel:BYTE_0 dst_unused:UNUSED_PAD src0_sel:DWORD
	v_mul_f32_e32 v186, v90, v226
	v_mul_f32_e32 v187, v91, v227
	v_rndne_f32_e32 v186, v186
	v_rndne_f32_e32 v187, v187
	v_cvt_i32_f32_sdwa v190, v186 dst_sel:BYTE_1 dst_unused:UNUSED_PRESERVE src0_sel:DWORD
	v_cvt_i32_f32_sdwa v196, v187 dst_sel:BYTE_1 dst_unused:UNUSED_PRESERVE src0_sel:DWORD
	v_mul_f32_e32 v186, v94, v226
	v_mul_f32_e32 v187, v95, v227
	v_rndne_f32_e32 v186, v186
	v_rndne_f32_e32 v187, v187
	v_cvt_i32_f32_sdwa v190, v186 dst_sel:BYTE_2 dst_unused:UNUSED_PRESERVE src0_sel:DWORD
	v_cvt_i32_f32_sdwa v196, v187 dst_sel:BYTE_2 dst_unused:UNUSED_PRESERVE src0_sel:DWORD
	v_mul_f32_e32 v186, v98, v226
	v_mul_f32_e32 v187, v99, v227
	v_rndne_f32_e32 v186, v186
	v_rndne_f32_e32 v187, v187
	v_cvt_i32_f32_sdwa v190, v186 dst_sel:BYTE_3 dst_unused:UNUSED_PRESERVE src0_sel:DWORD
	v_cvt_i32_f32_sdwa v196, v187 dst_sel:BYTE_3 dst_unused:UNUSED_PRESERVE src0_sel:DWORD
	s_nop 0
	ds_write_b32 v139, v190 offset:320
	ds_write_b32 v139, v196 offset:832
	v_mul_f32_e32 v186, v88, v228
	v_mul_f32_e32 v187, v89, v229
	v_rndne_f32_e32 v186, v186
	v_rndne_f32_e32 v187, v187
	v_cvt_i32_f32_sdwa v190, v186 dst_sel:BYTE_0 dst_unused:UNUSED_PAD src0_sel:DWORD
	v_cvt_i32_f32_sdwa v196, v187 dst_sel:BYTE_0 dst_unused:UNUSED_PAD src0_sel:DWORD
	v_mul_f32_e32 v186, v92, v228
	v_mul_f32_e32 v187, v93, v229
	v_rndne_f32_e32 v186, v186
	v_rndne_f32_e32 v187, v187
	v_cvt_i32_f32_sdwa v190, v186 dst_sel:BYTE_1 dst_unused:UNUSED_PRESERVE src0_sel:DWORD
	v_cvt_i32_f32_sdwa v196, v187 dst_sel:BYTE_1 dst_unused:UNUSED_PRESERVE src0_sel:DWORD
	v_mul_f32_e32 v186, v96, v228
	v_mul_f32_e32 v187, v97, v229
	v_rndne_f32_e32 v186, v186
	v_rndne_f32_e32 v187, v187
	v_cvt_i32_f32_sdwa v190, v186 dst_sel:BYTE_2 dst_unused:UNUSED_PRESERVE src0_sel:DWORD
	v_cvt_i32_f32_sdwa v196, v187 dst_sel:BYTE_2 dst_unused:UNUSED_PRESERVE src0_sel:DWORD
	v_mul_f32_e32 v186, v100, v228
	v_mul_f32_e32 v187, v101, v229
	v_rndne_f32_e32 v186, v186
	v_rndne_f32_e32 v187, v187
	v_cvt_i32_f32_sdwa v190, v186 dst_sel:BYTE_3 dst_unused:UNUSED_PRESERVE src0_sel:DWORD
	v_cvt_i32_f32_sdwa v196, v187 dst_sel:BYTE_3 dst_unused:UNUSED_PRESERVE src0_sel:DWORD
	s_nop 0
	ds_write_b32 v139, v190 offset:1344
	ds_write_b32 v139, v196 offset:1856
	s_cmp_ge_u32 s10, 0x200
	s_cbranch_scc1 .Lc16_gates_nopf_5
	global_load_dwordx4 v[86:89], v138, s[56:57]
	s_add_u32 s56, s56, 0x8000
	s_addc_u32 s57, s57, 0
	global_load_dwordx4 v[90:93], v138, s[56:57]
	s_add_u32 s56, s56, 0x8000
	s_addc_u32 s57, s57, 0
	global_load_dwordx4 v[94:97], v138, s[56:57]
	s_add_u32 s56, s56, 0x8000
	s_addc_u32 s57, s57, 0
	global_load_dwordx4 v[98:101], v138, s[56:57]
	s_add_u32 s56, s56, 0x1e8000
	s_addc_u32 s57, s57, 0
.Lc16_gates_nopf_5:
	v_mul_f32_e32 v186, v102, v226
	v_mul_f32_e32 v187, v103, v227
	v_rndne_f32_e32 v186, v186
	v_rndne_f32_e32 v187, v187
	v_cvt_i32_f32_sdwa v190, v186 dst_sel:BYTE_0 dst_unused:UNUSED_PAD src0_sel:DWORD
	v_cvt_i32_f32_sdwa v196, v187 dst_sel:BYTE_0 dst_unused:UNUSED_PAD src0_sel:DWORD
	v_mul_f32_e32 v186, v106, v226
	v_mul_f32_e32 v187, v107, v227
	v_rndne_f32_e32 v186, v186
	v_rndne_f32_e32 v187, v187
	v_cvt_i32_f32_sdwa v190, v186 dst_sel:BYTE_1 dst_unused:UNUSED_PRESERVE src0_sel:DWORD
	v_cvt_i32_f32_sdwa v196, v187 dst_sel:BYTE_1 dst_unused:UNUSED_PRESERVE src0_sel:DWORD
	v_mul_f32_e32 v186, v110, v226
	v_mul_f32_e32 v187, v111, v227
	v_rndne_f32_e32 v186, v186
	v_rndne_f32_e32 v187, v187
	v_cvt_i32_f32_sdwa v190, v186 dst_sel:BYTE_2 dst_unused:UNUSED_PRESERVE src0_sel:DWORD
	v_cvt_i32_f32_sdwa v196, v187 dst_sel:BYTE_2 dst_unused:UNUSED_PRESERVE src0_sel:DWORD
	v_mul_f32_e32 v186, v114, v226
	v_mul_f32_e32 v187, v115, v227
	v_rndne_f32_e32 v186, v186
	v_rndne_f32_e32 v187, v187
	v_cvt_i32_f32_sdwa v190, v186 dst_sel:BYTE_3 dst_unused:UNUSED_PRESERVE src0_sel:DWORD
	v_cvt_i32_f32_sdwa v196, v187 dst_sel:BYTE_3 dst_unused:UNUSED_PRESERVE src0_sel:DWORD
	s_nop 0
	ds_write_b32 v139, v190 offset:384
	ds_write_b32 v139, v196 offset:896
	v_mul_f32_e32 v186, v104, v228
	v_mul_f32_e32 v187, v105, v229
	v_rndne_f32_e32 v186, v186
	v_rndne_f32_e32 v187, v187
	v_cvt_i32_f32_sdwa v190, v186 dst_sel:BYTE_0 dst_unused:UNUSED_PAD src0_sel:DWORD
	v_cvt_i32_f32_sdwa v196, v187 dst_sel:BYTE_0 dst_unused:UNUSED_PAD src0_sel:DWORD
	v_mul_f32_e32 v186, v108, v228
	v_mul_f32_e32 v187, v109, v229
	v_rndne_f32_e32 v186, v186
	v_rndne_f32_e32 v187, v187
	v_cvt_i32_f32_sdwa v190, v186 dst_sel:BYTE_1 dst_unused:UNUSED_PRESERVE src0_sel:DWORD
	v_cvt_i32_f32_sdwa v196, v187 dst_sel:BYTE_1 dst_unused:UNUSED_PRESERVE src0_sel:DWORD
	v_mul_f32_e32 v186, v112, v228
	v_mul_f32_e32 v187, v113, v229
	v_rndne_f32_e32 v186, v186
	v_rndne_f32_e32 v187, v187
	v_cvt_i32_f32_sdwa v190, v186 dst_sel:BYTE_2 dst_unused:UNUSED_PRESERVE src0_sel:DWORD
	v_cvt_i32_f32_sdwa v196, v187 dst_sel:BYTE_2 dst_unused:UNUSED_PRESERVE src0_sel:DWORD
	v_mul_f32_e32 v186, v116, v228
	v_mul_f32_e32 v187, v117, v229
	v_rndne_f32_e32 v186, v186
	v_rndne_f32_e32 v187, v187
	v_cvt_i32_f32_sdwa v190, v186 dst_sel:BYTE_3 dst_unused:UNUSED_PRESERVE src0_sel:DWORD
	v_cvt_i32_f32_sdwa v196, v187 dst_sel:BYTE_3 dst_unused:UNUSED_PRESERVE src0_sel:DWORD
	s_nop 0
	ds_write_b32 v139, v190 offset:1408
	ds_write_b32 v139, v196 offset:1920
	s_cmp_ge_u32 s10, 0x200
	s_cbranch_scc1 .Lc16_gates_nopf_6
	global_load_dwordx4 v[102:105], v138, s[56:57]
	s_add_u32 s56, s56, 0x8000
	s_addc_u32 s57, s57, 0
	global_load_dwordx4 v[106:109], v138, s[56:57]
	s_add_u32 s56, s56, 0x8000
	s_addc_u32 s57, s57, 0
	global_load_dwordx4 v[110:113], v138, s[56:57]
	s_add_u32 s56, s56, 0x8000
	s_addc_u32 s57, s57, 0
	global_load_dwordx4 v[114:117], v138, s[56:57]
	s_add_u32 s56, s56, 0x1e8000
	s_addc_u32 s57, s57, 0
.Lc16_gates_nopf_6:
	v_mul_f32_e32 v186, v118, v226
	v_mul_f32_e32 v187, v119, v227
	v_rndne_f32_e32 v186, v186
	v_rndne_f32_e32 v187, v187
	v_cvt_i32_f32_sdwa v190, v186 dst_sel:BYTE_0 dst_unused:UNUSED_PAD src0_sel:DWORD
	v_cvt_i32_f32_sdwa v196, v187 dst_sel:BYTE_0 dst_unused:UNUSED_PAD src0_sel:DWORD
	v_mul_f32_e32 v186, v122, v226
	v_mul_f32_e32 v187, v123, v227
	v_rndne_f32_e32 v186, v186
	v_rndne_f32_e32 v187, v187
	v_cvt_i32_f32_sdwa v190, v186 dst_sel:BYTE_1 dst_unused:UNUSED_PRESERVE src0_sel:DWORD
	v_cvt_i32_f32_sdwa v196, v187 dst_sel:BYTE_1 dst_unused:UNUSED_PRESERVE src0_sel:DWORD
	v_mul_f32_e32 v186, v126, v226
	v_mul_f32_e32 v187, v127, v227
	v_rndne_f32_e32 v186, v186
	v_rndne_f32_e32 v187, v187
	v_cvt_i32_f32_sdwa v190, v186 dst_sel:BYTE_2 dst_unused:UNUSED_PRESERVE src0_sel:DWORD
	v_cvt_i32_f32_sdwa v196, v187 dst_sel:BYTE_2 dst_unused:UNUSED_PRESERVE src0_sel:DWORD
	v_mul_f32_e32 v186, v130, v226
	v_mul_f32_e32 v187, v131, v227
	v_rndne_f32_e32 v186, v186
	v_rndne_f32_e32 v187, v187
	v_cvt_i32_f32_sdwa v190, v186 dst_sel:BYTE_3 dst_unused:UNUSED_PRESERVE src0_sel:DWORD
	v_cvt_i32_f32_sdwa v196, v187 dst_sel:BYTE_3 dst_unused:UNUSED_PRESERVE src0_sel:DWORD
	s_nop 0
	ds_write_b32 v139, v190 offset:448
	ds_write_b32 v139, v196 offset:960
	v_mul_f32_e32 v186, v120, v228
	v_mul_f32_e32 v187, v121, v229
	v_rndne_f32_e32 v186, v186
	v_rndne_f32_e32 v187, v187
	v_cvt_i32_f32_sdwa v190, v186 dst_sel:BYTE_0 dst_unused:UNUSED_PAD src0_sel:DWORD
	v_cvt_i32_f32_sdwa v196, v187 dst_sel:BYTE_0 dst_unused:UNUSED_PAD src0_sel:DWORD
	v_mul_f32_e32 v186, v124, v228
	v_mul_f32_e32 v187, v125, v229
	v_rndne_f32_e32 v186, v186
	v_rndne_f32_e32 v187, v187
	v_cvt_i32_f32_sdwa v190, v186 dst_sel:BYTE_1 dst_unused:UNUSED_PRESERVE src0_sel:DWORD
	v_cvt_i32_f32_sdwa v196, v187 dst_sel:BYTE_1 dst_unused:UNUSED_PRESERVE src0_sel:DWORD
	v_mul_f32_e32 v186, v128, v228
	v_mul_f32_e32 v187, v129, v229
	v_rndne_f32_e32 v186, v186
	v_rndne_f32_e32 v187, v187
	v_cvt_i32_f32_sdwa v190, v186 dst_sel:BYTE_2 dst_unused:UNUSED_PRESERVE src0_sel:DWORD
	v_cvt_i32_f32_sdwa v196, v187 dst_sel:BYTE_2 dst_unused:UNUSED_PRESERVE src0_sel:DWORD
	v_mul_f32_e32 v186, v132, v228
	v_mul_f32_e32 v187, v133, v229
	v_rndne_f32_e32 v186, v186
	v_rndne_f32_e32 v187, v187
	v_cvt_i32_f32_sdwa v190, v186 dst_sel:BYTE_3 dst_unused:UNUSED_PRESERVE src0_sel:DWORD
	v_cvt_i32_f32_sdwa v196, v187 dst_sel:BYTE_3 dst_unused:UNUSED_PRESERVE src0_sel:DWORD
	s_nop 0
	ds_write_b32 v139, v190 offset:1472
	ds_write_b32 v139, v196 offset:1984
	s_cmp_ge_u32 s10, 0x200
	s_cbranch_scc1 .Lc16_gates_nopf_7
	global_load_dwordx4 v[118:121], v138, s[56:57]
	s_add_u32 s56, s56, 0x8000
	s_addc_u32 s57, s57, 0
	global_load_dwordx4 v[122:125], v138, s[56:57]
	s_add_u32 s56, s56, 0x8000
	s_addc_u32 s57, s57, 0
	global_load_dwordx4 v[126:129], v138, s[56:57]
	s_add_u32 s56, s56, 0x8000
	s_addc_u32 s57, s57, 0
	global_load_dwordx4 v[130:133], v138, s[56:57]

.Lc16_ffn1_nocm:
	v_div_scale_f32 v175, s[70:71], v220, v220, s74
	v_rcp_f32_e32 v176, v175
	s_nop 0
	v_fma_f32 v177, -v175, v176, 1.0
	v_fmac_f32_e32 v176, v177, v176
	v_div_scale_f32 v177, vcc, s74, v220, s74
	v_mul_f32_e32 v178, v177, v176
	v_fma_f32 v180, -v175, v178, v177
	v_fmac_f32_e32 v178, v180, v176
	v_fma_f32 v175, -v175, v178, v177
	s_nop 0
	v_div_fmas_f32 v175, v175, v176, v178
	v_div_fixup_f32 v175, v175, v220, s74
	v_cmp_lt_f32_e32 vcc, 0, v220
	s_nop 1
	v_cndmask_b32_e32 v226, 0, v175, vcc
	v_div_scale_f32 v175, s[70:71], v221, v221, s74
	v_rcp_f32_e32 v176, v175
	s_nop 0
	v_fma_f32 v177, -v175, v176, 1.0
	v_fmac_f32_e32 v176, v177, v176
	v_div_scale_f32 v177, vcc, s74, v221, s74
	v_mul_f32_e32 v178, v177, v176
	v_fma_f32 v180, -v175, v178, v177
	v_fmac_f32_e32 v178, v180, v176
	v_fma_f32 v175, -v175, v178, v177
	s_nop 0
	v_div_fmas_f32 v175, v175, v176, v178
	v_div_fixup_f32 v175, v175, v221, s74
	v_cmp_lt_f32_e32 vcc, 0, v221
	s_nop 1
	v_cndmask_b32_e32 v227, 0, v175, vcc
	v_div_scale_f32 v175, s[70:71], v222, v222, s74
	v_rcp_f32_e32 v176, v175
	s_nop 0
	v_fma_f32 v177, -v175, v176, 1.0
	v_fmac_f32_e32 v176, v177, v176
	v_div_scale_f32 v177, vcc, s74, v222, s74
	v_mul_f32_e32 v178, v177, v176
	v_fma_f32 v180, -v175, v178, v177
	v_fmac_f32_e32 v178, v180, v176
	v_fma_f32 v175, -v175, v178, v177
	s_nop 0
	v_div_fmas_f32 v175, v175, v176, v178
	v_div_fixup_f32 v175, v175, v222, s74
	v_cmp_lt_f32_e32 vcc, 0, v222
	s_nop 1
	v_cndmask_b32_e32 v228, 0, v175, vcc
	v_div_scale_f32 v175, s[70:71], v223, v223, s74
	v_rcp_f32_e32 v176, v175
	s_nop 0
	v_fma_f32 v177, -v175, v176, 1.0
	v_fmac_f32_e32 v176, v177, v176
	v_div_scale_f32 v177, vcc, s74, v223, s74
	v_mul_f32_e32 v178, v177, v176
	v_fma_f32 v180, -v175, v178, v177
	v_fmac_f32_e32 v178, v180, v176
	v_fma_f32 v175, -v175, v178, v177
	s_nop 0
	v_div_fmas_f32 v175, v175, v176, v178
	v_div_fixup_f32 v175, v175, v223, s74
	v_cmp_lt_f32_e32 vcc, 0, v223
	s_nop 1
	v_cndmask_b32_e32 v229, 0, v175, vcc
	s_add_u32 s10, s0, s33
	s_lshl_b32 s3, s10, 6
	s_add_u32 s56, s48, s3
	s_addc_u32 s57, s49, 0
	v_mul_f32_e32 v186, v6, v226
	v_mul_f32_e32 v187, v7, v227
	v_rndne_f32_e32 v186, v186
	v_rndne_f32_e32 v187, v187
	v_cvt_i32_f32_sdwa v190, v186 dst_sel:BYTE_0 dst_unused:UNUSED_PAD src0_sel:DWORD
	v_cvt_i32_f32_sdwa v196, v187 dst_sel:BYTE_0 dst_unused:UNUSED_PAD src0_sel:DWORD
	v_mul_f32_e32 v186, v10, v226
	v_mul_f32_e32 v187, v11, v227
	v_rndne_f32_e32 v186, v186
	v_rndne_f32_e32 v187, v187
	v_cvt_i32_f32_sdwa v190, v186 dst_sel:BYTE_1 dst_unused:UNUSED_PRESERVE src0_sel:DWORD
	v_cvt_i32_f32_sdwa v196, v187 dst_sel:BYTE_1 dst_unused:UNUSED_PRESERVE src0_sel:DWORD
	v_mul_f32_e32 v186, v14, v226
	v_mul_f32_e32 v187, v15, v227
	v_rndne_f32_e32 v186, v186
	v_rndne_f32_e32 v187, v187
	v_cvt_i32_f32_sdwa v190, v186 dst_sel:BYTE_2 dst_unused:UNUSED_PRESERVE src0_sel:DWORD
	v_cvt_i32_f32_sdwa v196, v187 dst_sel:BYTE_2 dst_unused:UNUSED_PRESERVE src0_sel:DWORD
	v_mul_f32_e32 v186, v18, v226
	v_mul_f32_e32 v187, v19, v227
	v_rndne_f32_e32 v186, v186
	v_rndne_f32_e32 v187, v187
	v_cvt_i32_f32_sdwa v190, v186 dst_sel:BYTE_3 dst_unused:UNUSED_PRESERVE src0_sel:DWORD
	v_cvt_i32_f32_sdwa v196, v187 dst_sel:BYTE_3 dst_unused:UNUSED_PRESERVE src0_sel:DWORD
	s_nop 0
	ds_write_b32 v139, v190 offset:0
	ds_write_b32 v139, v196 offset:512
	v_mul_f32_e32 v186, v8, v228
	v_mul_f32_e32 v187, v9, v229
	v_rndne_f32_e32 v186, v186
	v_rndne_f32_e32 v187, v187
	v_cvt_i32_f32_sdwa v190, v186 dst_sel:BYTE_0 dst_unused:UNUSED_PAD src0_sel:DWORD
	v_cvt_i32_f32_sdwa v196, v187 dst_sel:BYTE_0 dst_unused:UNUSED_PAD src0_sel:DWORD
	v_mul_f32_e32 v186, v12, v228
	v_mul_f32_e32 v187, v13, v229
	v_rndne_f32_e32 v186, v186
	v_rndne_f32_e32 v187, v187
	v_cvt_i32_f32_sdwa v190, v186 dst_sel:BYTE_1 dst_unused:UNUSED_PRESERVE src0_sel:DWORD
	v_cvt_i32_f32_sdwa v196, v187 dst_sel:BYTE_1 dst_unused:UNUSED_PRESERVE src0_sel:DWORD
	v_mul_f32_e32 v186, v16, v228
	v_mul_f32_e32 v187, v17, v229
	v_rndne_f32_e32 v186, v186
	v_rndne_f32_e32 v187, v187
	v_cvt_i32_f32_sdwa v190, v186 dst_sel:BYTE_2 dst_unused:UNUSED_PRESERVE src0_sel:DWORD
	v_cvt_i32_f32_sdwa v196, v187 dst_sel:BYTE_2 dst_unused:UNUSED_PRESERVE src0_sel:DWORD
	v_mul_f32_e32 v186, v20, v228
	v_mul_f32_e32 v187, v21, v229
	v_rndne_f32_e32 v186, v186
	v_rndne_f32_e32 v187, v187
	v_cvt_i32_f32_sdwa v190, v186 dst_sel:BYTE_3 dst_unused:UNUSED_PRESERVE src0_sel:DWORD
	v_cvt_i32_f32_sdwa v196, v187 dst_sel:BYTE_3 dst_unused:UNUSED_PRESERVE src0_sel:DWORD
	s_nop 0
	ds_write_b32 v139, v190 offset:1024
	ds_write_b32 v139, v196 offset:1536
	s_cmp_ge_u32 s10, 0x560
	s_cbranch_scc1 .Lc16_ffn1_nopf_0
	global_load_dwordx4 v[6:9], v138, s[56:57]
	s_add_u32 s56, s56, 0x15800
	s_addc_u32 s57, s57, 0
	global_load_dwordx4 v[10:13], v138, s[56:57]
	s_add_u32 s56, s56, 0x15800
	s_addc_u32 s57, s57, 0
	global_load_dwordx4 v[14:17], v138, s[56:57]
	s_add_u32 s56, s56, 0x15800
	s_addc_u32 s57, s57, 0
	global_load_dwordx4 v[18:21], v138, s[56:57]
	s_add_u32 s56, s56, 0x51f800
	s_addc_u32 s57, s57, 0
.Lc16_ffn1_nopf_0:
	v_mul_f32_e32 v186, v22, v226
	v_mul_f32_e32 v187, v23, v227
	v_rndne_f32_e32 v186, v186
	v_rndne_f32_e32 v187, v187
	v_cvt_i32_f32_sdwa v190, v186 dst_sel:BYTE_0 dst_unused:UNUSED_PAD src0_sel:DWORD
	v_cvt_i32_f32_sdwa v196, v187 dst_sel:BYTE_0 dst_unused:UNUSED_PAD src0_sel:DWORD
	v_mul_f32_e32 v186, v26, v226
	v_mul_f32_e32 v187, v27, v227
	v_rndne_f32_e32 v186, v186
	v_rndne_f32_e32 v187, v187
	v_cvt_i32_f32_sdwa v190, v186 dst_sel:BYTE_1 dst_unused:UNUSED_PRESERVE src0_sel:DWORD
	v_cvt_i32_f32_sdwa v196, v187 dst_sel:BYTE_1 dst_unused:UNUSED_PRESERVE src0_sel:DWORD
	v_mul_f32_e32 v186, v30, v226
	v_mul_f32_e32 v187, v31, v227
	v_rndne_f32_e32 v186, v186
	v_rndne_f32_e32 v187, v187
	v_cvt_i32_f32_sdwa v190, v186 dst_sel:BYTE_2 dst_unused:UNUSED_PRESERVE src0_sel:DWORD
	v_cvt_i32_f32_sdwa v196, v187 dst_sel:BYTE_2 dst_unused:UNUSED_PRESERVE src0_sel:DWORD
	v_mul_f32_e32 v186, v34, v226
	v_mul_f32_e32 v187, v35, v227
	v_rndne_f32_e32 v186, v186
	v_rndne_f32_e32 v187, v187
	v_cvt_i32_f32_sdwa v190, v186 dst_sel:BYTE_3 dst_unused:UNUSED_PRESERVE src0_sel:DWORD
	v_cvt_i32_f32_sdwa v196, v187 dst_sel:BYTE_3 dst_unused:UNUSED_PRESERVE src0_sel:DWORD
	s_nop 0
	ds_write_b32 v139, v190 offset:64
	ds_write_b32 v139, v196 offset:576
	v_mul_f32_e32 v186, v24, v228
	v_mul_f32_e32 v187, v25, v229
	v_rndne_f32_e32 v186, v186
	v_rndne_f32_e32 v187, v187
	v_cvt_i32_f32_sdwa v190, v186 dst_sel:BYTE_0 dst_unused:UNUSED_PAD src0_sel:DWORD
	v_cvt_i32_f32_sdwa v196, v187 dst_sel:BYTE_0 dst_unused:UNUSED_PAD src0_sel:DWORD
	v_mul_f32_e32 v186, v28, v228
	v_mul_f32_e32 v187, v29, v229
	v_rndne_f32_e32 v186, v186
	v_rndne_f32_e32 v187, v187
	v_cvt_i32_f32_sdwa v190, v186 dst_sel:BYTE_1 dst_unused:UNUSED_PRESERVE src0_sel:DWORD
	v_cvt_i32_f32_sdwa v196, v187 dst_sel:BYTE_1 dst_unused:UNUSED_PRESERVE src0_sel:DWORD
	v_mul_f32_e32 v186, v32, v228
	v_mul_f32_e32 v187, v33, v229
	v_rndne_f32_e32 v186, v186
	v_rndne_f32_e32 v187, v187
	v_cvt_i32_f32_sdwa v190, v186 dst_sel:BYTE_2 dst_unused:UNUSED_PRESERVE src0_sel:DWORD
	v_cvt_i32_f32_sdwa v196, v187 dst_sel:BYTE_2 dst_unused:UNUSED_PRESERVE src0_sel:DWORD
	v_mul_f32_e32 v186, v36, v228
	v_mul_f32_e32 v187, v37, v229
	v_rndne_f32_e32 v186, v186
	v_rndne_f32_e32 v187, v187
	v_cvt_i32_f32_sdwa v190, v186 dst_sel:BYTE_3 dst_unused:UNUSED_PRESERVE src0_sel:DWORD
	v_cvt_i32_f32_sdwa v196, v187 dst_sel:BYTE_3 dst_unused:UNUSED_PRESERVE src0_sel:DWORD
	s_nop 0
	ds_write_b32 v139, v190 offset:1088
	ds_write_b32 v139, v196 offset:1600
	s_cmp_ge_u32 s10, 0x560
	s_cbranch_scc1 .Lc16_ffn1_nopf_1
	global_load_dwordx4 v[22:25], v138, s[56:57]
	s_add_u32 s56, s56, 0x15800
	s_addc_u32 s57, s57, 0
	global_load_dwordx4 v[26:29], v138, s[56:57]
	s_add_u32 s56, s56, 0x15800
	s_addc_u32 s57, s57, 0
	global_load_dwordx4 v[30:33], v138, s[56:57]
	s_add_u32 s56, s56, 0x15800
	s_addc_u32 s57, s57, 0
	global_load_dwordx4 v[34:37], v138, s[56:57]
	s_add_u32 s56, s56, 0x51f800
	s_addc_u32 s57, s57, 0
.Lc16_ffn1_nopf_1:
	v_mul_f32_e32 v186, v38, v226
	v_mul_f32_e32 v187, v39, v227
	v_rndne_f32_e32 v186, v186
	v_rndne_f32_e32 v187, v187
	v_cvt_i32_f32_sdwa v190, v186 dst_sel:BYTE_0 dst_unused:UNUSED_PAD src0_sel:DWORD
	v_cvt_i32_f32_sdwa v196, v187 dst_sel:BYTE_0 dst_unused:UNUSED_PAD src0_sel:DWORD
	v_mul_f32_e32 v186, v42, v226
	v_mul_f32_e32 v187, v43, v227
	v_rndne_f32_e32 v186, v186
	v_rndne_f32_e32 v187, v187
	v_cvt_i32_f32_sdwa v190, v186 dst_sel:BYTE_1 dst_unused:UNUSED_PRESERVE src0_sel:DWORD
	v_cvt_i32_f32_sdwa v196, v187 dst_sel:BYTE_1 dst_unused:UNUSED_PRESERVE src0_sel:DWORD
	v_mul_f32_e32 v186, v46, v226
	v_mul_f32_e32 v187, v47, v227
	v_rndne_f32_e32 v186, v186
	v_rndne_f32_e32 v187, v187
	v_cvt_i32_f32_sdwa v190, v186 dst_sel:BYTE_2 dst_unused:UNUSED_PRESERVE src0_sel:DWORD
	v_cvt_i32_f32_sdwa v196, v187 dst_sel:BYTE_2 dst_unused:UNUSED_PRESERVE src0_sel:DWORD
	v_mul_f32_e32 v186, v50, v226
	v_mul_f32_e32 v187, v51, v227
	v_rndne_f32_e32 v186, v186
	v_rndne_f32_e32 v187, v187
	v_cvt_i32_f32_sdwa v190, v186 dst_sel:BYTE_3 dst_unused:UNUSED_PRESERVE src0_sel:DWORD
	v_cvt_i32_f32_sdwa v196, v187 dst_sel:BYTE_3 dst_unused:UNUSED_PRESERVE src0_sel:DWORD
	s_nop 0
	ds_write_b32 v139, v190 offset:128
	ds_write_b32 v139, v196 offset:640
	v_mul_f32_e32 v186, v40, v228
	v_mul_f32_e32 v187, v41, v229
	v_rndne_f32_e32 v186, v186
	v_rndne_f32_e32 v187, v187
	v_cvt_i32_f32_sdwa v190, v186 dst_sel:BYTE_0 dst_unused:UNUSED_PAD src0_sel:DWORD
	v_cvt_i32_f32_sdwa v196, v187 dst_sel:BYTE_0 dst_unused:UNUSED_PAD src0_sel:DWORD
	v_mul_f32_e32 v186, v44, v228
	v_mul_f32_e32 v187, v45, v229
	v_rndne_f32_e32 v186, v186
	v_rndne_f32_e32 v187, v187
	v_cvt_i32_f32_sdwa v190, v186 dst_sel:BYTE_1 dst_unused:UNUSED_PRESERVE src0_sel:DWORD
	v_cvt_i32_f32_sdwa v196, v187 dst_sel:BYTE_1 dst_unused:UNUSED_PRESERVE src0_sel:DWORD
	v_mul_f32_e32 v186, v48, v228
	v_mul_f32_e32 v187, v49, v229
	v_rndne_f32_e32 v186, v186
	v_rndne_f32_e32 v187, v187
	v_cvt_i32_f32_sdwa v190, v186 dst_sel:BYTE_2 dst_unused:UNUSED_PRESERVE src0_sel:DWORD
	v_cvt_i32_f32_sdwa v196, v187 dst_sel:BYTE_2 dst_unused:UNUSED_PRESERVE src0_sel:DWORD
	v_mul_f32_e32 v186, v52, v228
	v_mul_f32_e32 v187, v53, v229
	v_rndne_f32_e32 v186, v186
	v_rndne_f32_e32 v187, v187
	v_cvt_i32_f32_sdwa v190, v186 dst_sel:BYTE_3 dst_unused:UNUSED_PRESERVE src0_sel:DWORD
	v_cvt_i32_f32_sdwa v196, v187 dst_sel:BYTE_3 dst_unused:UNUSED_PRESERVE src0_sel:DWORD
	s_nop 0
	ds_write_b32 v139, v190 offset:1152
	ds_write_b32 v139, v196 offset:1664
	s_cmp_ge_u32 s10, 0x560
	s_cbranch_scc1 .Lc16_ffn1_nopf_2
	global_load_dwordx4 v[38:41], v138, s[56:57]
	s_add_u32 s56, s56, 0x15800
	s_addc_u32 s57, s57, 0
	global_load_dwordx4 v[42:45], v138, s[56:57]
	s_add_u32 s56, s56, 0x15800
	s_addc_u32 s57, s57, 0
	global_load_dwordx4 v[46:49], v138, s[56:57]
	s_add_u32 s56, s56, 0x15800
	s_addc_u32 s57, s57, 0
	global_load_dwordx4 v[50:53], v138, s[56:57]
	s_add_u32 s56, s56, 0x51f800
	s_addc_u32 s57, s57, 0
.Lc16_ffn1_nopf_2:
	v_mul_f32_e32 v186, v54, v226
	v_mul_f32_e32 v187, v55, v227
	v_rndne_f32_e32 v186, v186
	v_rndne_f32_e32 v187, v187
	v_cvt_i32_f32_sdwa v190, v186 dst_sel:BYTE_0 dst_unused:UNUSED_PAD src0_sel:DWORD
	v_cvt_i32_f32_sdwa v196, v187 dst_sel:BYTE_0 dst_unused:UNUSED_PAD src0_sel:DWORD
	v_mul_f32_e32 v186, v58, v226
	v_mul_f32_e32 v187, v59, v227
	v_rndne_f32_e32 v186, v186
	v_rndne_f32_e32 v187, v187
	v_cvt_i32_f32_sdwa v190, v186 dst_sel:BYTE_1 dst_unused:UNUSED_PRESERVE src0_sel:DWORD
	v_cvt_i32_f32_sdwa v196, v187 dst_sel:BYTE_1 dst_unused:UNUSED_PRESERVE src0_sel:DWORD
	v_mul_f32_e32 v186, v62, v226
	v_mul_f32_e32 v187, v63, v227
	v_rndne_f32_e32 v186, v186
	v_rndne_f32_e32 v187, v187
	v_cvt_i32_f32_sdwa v190, v186 dst_sel:BYTE_2 dst_unused:UNUSED_PRESERVE src0_sel:DWORD
	v_cvt_i32_f32_sdwa v196, v187 dst_sel:BYTE_2 dst_unused:UNUSED_PRESERVE src0_sel:DWORD
	v_mul_f32_e32 v186, v66, v226
	v_mul_f32_e32 v187, v67, v227
	v_rndne_f32_e32 v186, v186
	v_rndne_f32_e32 v187, v187
	v_cvt_i32_f32_sdwa v190, v186 dst_sel:BYTE_3 dst_unused:UNUSED_PRESERVE src0_sel:DWORD
	v_cvt_i32_f32_sdwa v196, v187 dst_sel:BYTE_3 dst_unused:UNUSED_PRESERVE src0_sel:DWORD
	s_nop 0
	ds_write_b32 v139, v190 offset:192
	ds_write_b32 v139, v196 offset:704
	v_mul_f32_e32 v186, v56, v228
	v_mul_f32_e32 v187, v57, v229
	v_rndne_f32_e32 v186, v186
	v_rndne_f32_e32 v187, v187
	v_cvt_i32_f32_sdwa v190, v186 dst_sel:BYTE_0 dst_unused:UNUSED_PAD src0_sel:DWORD
	v_cvt_i32_f32_sdwa v196, v187 dst_sel:BYTE_0 dst_unused:UNUSED_PAD src0_sel:DWORD
	v_mul_f32_e32 v186, v60, v228
	v_mul_f32_e32 v187, v61, v229
	v_rndne_f32_e32 v186, v186
	v_rndne_f32_e32 v187, v187
	v_cvt_i32_f32_sdwa v190, v186 dst_sel:BYTE_1 dst_unused:UNUSED_PRESERVE src0_sel:DWORD
	v_cvt_i32_f32_sdwa v196, v187 dst_sel:BYTE_1 dst_unused:UNUSED_PRESERVE src0_sel:DWORD
	v_mul_f32_e32 v186, v64, v228
	v_mul_f32_e32 v187, v65, v229
	v_rndne_f32_e32 v186, v186
	v_rndne_f32_e32 v187, v187
	v_cvt_i32_f32_sdwa v190, v186 dst_sel:BYTE_2 dst_unused:UNUSED_PRESERVE src0_sel:DWORD
	v_cvt_i32_f32_sdwa v196, v187 dst_sel:BYTE_2 dst_unused:UNUSED_PRESERVE src0_sel:DWORD
	v_mul_f32_e32 v186, v68, v228
	v_mul_f32_e32 v187, v69, v229
	v_rndne_f32_e32 v186, v186
	v_rndne_f32_e32 v187, v187
	v_cvt_i32_f32_sdwa v190, v186 dst_sel:BYTE_3 dst_unused:UNUSED_PRESERVE src0_sel:DWORD
	v_cvt_i32_f32_sdwa v196, v187 dst_sel:BYTE_3 dst_unused:UNUSED_PRESERVE src0_sel:DWORD
	s_nop 0
	ds_write_b32 v139, v190 offset:1216
	ds_write_b32 v139, v196 offset:1728
	s_cmp_ge_u32 s10, 0x560
	s_cbranch_scc1 .Lc16_ffn1_nopf_3
	global_load_dwordx4 v[54:57], v138, s[56:57]
	s_add_u32 s56, s56, 0x15800
	s_addc_u32 s57, s57, 0
	global_load_dwordx4 v[58:61], v138, s[56:57]
	s_add_u32 s56, s56, 0x15800
	s_addc_u32 s57, s57, 0
	global_load_dwordx4 v[62:65], v138, s[56:57]
	s_add_u32 s56, s56, 0x15800
	s_addc_u32 s57, s57, 0
	global_load_dwordx4 v[66:69], v138, s[56:57]
	s_add_u32 s56, s56, 0x51f800
	s_addc_u32 s57, s57, 0
.Lc16_ffn1_nopf_3:
	v_mul_f32_e32 v186, v70, v226
	v_mul_f32_e32 v187, v71, v227
	v_rndne_f32_e32 v186, v186
	v_rndne_f32_e32 v187, v187
	v_cvt_i32_f32_sdwa v190, v186 dst_sel:BYTE_0 dst_unused:UNUSED_PAD src0_sel:DWORD
	v_cvt_i32_f32_sdwa v196, v187 dst_sel:BYTE_0 dst_unused:UNUSED_PAD src0_sel:DWORD
	v_mul_f32_e32 v186, v74, v226
	v_mul_f32_e32 v187, v75, v227
	v_rndne_f32_e32 v186, v186
	v_rndne_f32_e32 v187, v187
	v_cvt_i32_f32_sdwa v190, v186 dst_sel:BYTE_1 dst_unused:UNUSED_PRESERVE src0_sel:DWORD
	v_cvt_i32_f32_sdwa v196, v187 dst_sel:BYTE_1 dst_unused:UNUSED_PRESERVE src0_sel:DWORD
	v_mul_f32_e32 v186, v78, v226
	v_mul_f32_e32 v187, v79, v227
	v_rndne_f32_e32 v186, v186
	v_rndne_f32_e32 v187, v187
	v_cvt_i32_f32_sdwa v190, v186 dst_sel:BYTE_2 dst_unused:UNUSED_PRESERVE src0_sel:DWORD
	v_cvt_i32_f32_sdwa v196, v187 dst_sel:BYTE_2 dst_unused:UNUSED_PRESERVE src0_sel:DWORD
	v_mul_f32_e32 v186, v82, v226
	v_mul_f32_e32 v187, v83, v227
	v_rndne_f32_e32 v186, v186
	v_rndne_f32_e32 v187, v187
	v_cvt_i32_f32_sdwa v190, v186 dst_sel:BYTE_3 dst_unused:UNUSED_PRESERVE src0_sel:DWORD
	v_cvt_i32_f32_sdwa v196, v187 dst_sel:BYTE_3 dst_unused:UNUSED_PRESERVE src0_sel:DWORD
	s_nop 0
	ds_write_b32 v139, v190 offset:256
	ds_write_b32 v139, v196 offset:768
	v_mul_f32_e32 v186, v72, v228
	v_mul_f32_e32 v187, v73, v229
	v_rndne_f32_e32 v186, v186
	v_rndne_f32_e32 v187, v187
	v_cvt_i32_f32_sdwa v190, v186 dst_sel:BYTE_0 dst_unused:UNUSED_PAD src0_sel:DWORD
	v_cvt_i32_f32_sdwa v196, v187 dst_sel:BYTE_0 dst_unused:UNUSED_PAD src0_sel:DWORD
	v_mul_f32_e32 v186, v76, v228
	v_mul_f32_e32 v187, v77, v229
	v_rndne_f32_e32 v186, v186
	v_rndne_f32_e32 v187, v187
	v_cvt_i32_f32_sdwa v190, v186 dst_sel:BYTE_1 dst_unused:UNUSED_PRESERVE src0_sel:DWORD
	v_cvt_i32_f32_sdwa v196, v187 dst_sel:BYTE_1 dst_unused:UNUSED_PRESERVE src0_sel:DWORD
	v_mul_f32_e32 v186, v80, v228
	v_mul_f32_e32 v187, v81, v229
	v_rndne_f32_e32 v186, v186
	v_rndne_f32_e32 v187, v187
	v_cvt_i32_f32_sdwa v190, v186 dst_sel:BYTE_2 dst_unused:UNUSED_PRESERVE src0_sel:DWORD
	v_cvt_i32_f32_sdwa v196, v187 dst_sel:BYTE_2 dst_unused:UNUSED_PRESERVE src0_sel:DWORD
	v_mul_f32_e32 v186, v84, v228
	v_mul_f32_e32 v187, v85, v229
	v_rndne_f32_e32 v186, v186
	v_rndne_f32_e32 v187, v187
	v_cvt_i32_f32_sdwa v190, v186 dst_sel:BYTE_3 dst_unused:UNUSED_PRESERVE src0_sel:DWORD
	v_cvt_i32_f32_sdwa v196, v187 dst_sel:BYTE_3 dst_unused:UNUSED_PRESERVE src0_sel:DWORD
	s_nop 0
	ds_write_b32 v139, v190 offset:1280
	ds_write_b32 v139, v196 offset:1792
	s_cmp_ge_u32 s10, 0x560
	s_cbranch_scc1 .Lc16_ffn1_nopf_4
	global_load_dwordx4 v[70:73], v138, s[56:57]
	s_add_u32 s56, s56, 0x15800
	s_addc_u32 s57, s57, 0
	global_load_dwordx4 v[74:77], v138, s[56:57]
	s_add_u32 s56, s56, 0x15800
	s_addc_u32 s57, s57, 0
	global_load_dwordx4 v[78:81], v138, s[56:57]
	s_add_u32 s56, s56, 0x15800
	s_addc_u32 s57, s57, 0
	global_load_dwordx4 v[82:85], v138, s[56:57]
	s_add_u32 s56, s56, 0x51f800
	s_addc_u32 s57, s57, 0
.Lc16_ffn1_nopf_4:
	v_mul_f32_e32 v186, v86, v226
	v_mul_f32_e32 v187, v87, v227
	v_rndne_f32_e32 v186, v186
	v_rndne_f32_e32 v187, v187
	v_cvt_i32_f32_sdwa v190, v186 dst_sel:BYTE_0 dst_unused:UNUSED_PAD src0_sel:DWORD
	v_cvt_i32_f32_sdwa v196, v187 dst_sel:BYTE_0 dst_unused:UNUSED_PAD src0_sel:DWORD
	v_mul_f32_e32 v186, v90, v226
	v_mul_f32_e32 v187, v91, v227
	v_rndne_f32_e32 v186, v186
	v_rndne_f32_e32 v187, v187
	v_cvt_i32_f32_sdwa v190, v186 dst_sel:BYTE_1 dst_unused:UNUSED_PRESERVE src0_sel:DWORD
	v_cvt_i32_f32_sdwa v196, v187 dst_sel:BYTE_1 dst_unused:UNUSED_PRESERVE src0_sel:DWORD
	v_mul_f32_e32 v186, v94, v226
	v_mul_f32_e32 v187, v95, v227
	v_rndne_f32_e32 v186, v186
	v_rndne_f32_e32 v187, v187
	v_cvt_i32_f32_sdwa v190, v186 dst_sel:BYTE_2 dst_unused:UNUSED_PRESERVE src0_sel:DWORD
	v_cvt_i32_f32_sdwa v196, v187 dst_sel:BYTE_2 dst_unused:UNUSED_PRESERVE src0_sel:DWORD
	v_mul_f32_e32 v186, v98, v226
	v_mul_f32_e32 v187, v99, v227
	v_rndne_f32_e32 v186, v186
	v_rndne_f32_e32 v187, v187
	v_cvt_i32_f32_sdwa v190, v186 dst_sel:BYTE_3 dst_unused:UNUSED_PRESERVE src0_sel:DWORD
	v_cvt_i32_f32_sdwa v196, v187 dst_sel:BYTE_3 dst_unused:UNUSED_PRESERVE src0_sel:DWORD
	s_nop 0
	ds_write_b32 v139, v190 offset:320
	ds_write_b32 v139, v196 offset:832
	v_mul_f32_e32 v186, v88, v228
	v_mul_f32_e32 v187, v89, v229
	v_rndne_f32_e32 v186, v186
	v_rndne_f32_e32 v187, v187
	v_cvt_i32_f32_sdwa v190, v186 dst_sel:BYTE_0 dst_unused:UNUSED_PAD src0_sel:DWORD
	v_cvt_i32_f32_sdwa v196, v187 dst_sel:BYTE_0 dst_unused:UNUSED_PAD src0_sel:DWORD
	v_mul_f32_e32 v186, v92, v228
	v_mul_f32_e32 v187, v93, v229
	v_rndne_f32_e32 v186, v186
	v_rndne_f32_e32 v187, v187
	v_cvt_i32_f32_sdwa v190, v186 dst_sel:BYTE_1 dst_unused:UNUSED_PRESERVE src0_sel:DWORD
	v_cvt_i32_f32_sdwa v196, v187 dst_sel:BYTE_1 dst_unused:UNUSED_PRESERVE src0_sel:DWORD
	v_mul_f32_e32 v186, v96, v228
	v_mul_f32_e32 v187, v97, v229
	v_rndne_f32_e32 v186, v186
	v_rndne_f32_e32 v187, v187
	v_cvt_i32_f32_sdwa v190, v186 dst_sel:BYTE_2 dst_unused:UNUSED_PRESERVE src0_sel:DWORD
	v_cvt_i32_f32_sdwa v196, v187 dst_sel:BYTE_2 dst_unused:UNUSED_PRESERVE src0_sel:DWORD
	v_mul_f32_e32 v186, v100, v228
	v_mul_f32_e32 v187, v101, v229
	v_rndne_f32_e32 v186, v186
	v_rndne_f32_e32 v187, v187
	v_cvt_i32_f32_sdwa v190, v186 dst_sel:BYTE_3 dst_unused:UNUSED_PRESERVE src0_sel:DWORD
	v_cvt_i32_f32_sdwa v196, v187 dst_sel:BYTE_3 dst_unused:UNUSED_PRESERVE src0_sel:DWORD
	s_nop 0
	ds_write_b32 v139, v190 offset:1344
	ds_write_b32 v139, v196 offset:1856
	s_cmp_ge_u32 s10, 0x560
	s_cbranch_scc1 .Lc16_ffn1_nopf_5
	global_load_dwordx4 v[86:89], v138, s[56:57]
	s_add_u32 s56, s56, 0x15800
	s_addc_u32 s57, s57, 0
	global_load_dwordx4 v[90:93], v138, s[56:57]
	s_add_u32 s56, s56, 0x15800
	s_addc_u32 s57, s57, 0
	global_load_dwordx4 v[94:97], v138, s[56:57]
	s_add_u32 s56, s56, 0x15800
	s_addc_u32 s57, s57, 0
	global_load_dwordx4 v[98:101], v138, s[56:57]
	s_add_u32 s56, s56, 0x51f800
	s_addc_u32 s57, s57, 0
.Lc16_ffn1_nopf_5:
	v_mul_f32_e32 v186, v102, v226
	v_mul_f32_e32 v187, v103, v227
	v_rndne_f32_e32 v186, v186
	v_rndne_f32_e32 v187, v187
	v_cvt_i32_f32_sdwa v190, v186 dst_sel:BYTE_0 dst_unused:UNUSED_PAD src0_sel:DWORD
	v_cvt_i32_f32_sdwa v196, v187 dst_sel:BYTE_0 dst_unused:UNUSED_PAD src0_sel:DWORD
	v_mul_f32_e32 v186, v106, v226
	v_mul_f32_e32 v187, v107, v227
	v_rndne_f32_e32 v186, v186
	v_rndne_f32_e32 v187, v187
	v_cvt_i32_f32_sdwa v190, v186 dst_sel:BYTE_1 dst_unused:UNUSED_PRESERVE src0_sel:DWORD
	v_cvt_i32_f32_sdwa v196, v187 dst_sel:BYTE_1 dst_unused:UNUSED_PRESERVE src0_sel:DWORD
	v_mul_f32_e32 v186, v110, v226
	v_mul_f32_e32 v187, v111, v227
	v_rndne_f32_e32 v186, v186
	v_rndne_f32_e32 v187, v187
	v_cvt_i32_f32_sdwa v190, v186 dst_sel:BYTE_2 dst_unused:UNUSED_PRESERVE src0_sel:DWORD
	v_cvt_i32_f32_sdwa v196, v187 dst_sel:BYTE_2 dst_unused:UNUSED_PRESERVE src0_sel:DWORD
	v_mul_f32_e32 v186, v114, v226
	v_mul_f32_e32 v187, v115, v227
	v_rndne_f32_e32 v186, v186
	v_rndne_f32_e32 v187, v187
	v_cvt_i32_f32_sdwa v190, v186 dst_sel:BYTE_3 dst_unused:UNUSED_PRESERVE src0_sel:DWORD
	v_cvt_i32_f32_sdwa v196, v187 dst_sel:BYTE_3 dst_unused:UNUSED_PRESERVE src0_sel:DWORD
	s_nop 0
	ds_write_b32 v139, v190 offset:384
	ds_write_b32 v139, v196 offset:896
	v_mul_f32_e32 v186, v104, v228
	v_mul_f32_e32 v187, v105, v229
	v_rndne_f32_e32 v186, v186
	v_rndne_f32_e32 v187, v187
	v_cvt_i32_f32_sdwa v190, v186 dst_sel:BYTE_0 dst_unused:UNUSED_PAD src0_sel:DWORD
	v_cvt_i32_f32_sdwa v196, v187 dst_sel:BYTE_0 dst_unused:UNUSED_PAD src0_sel:DWORD
	v_mul_f32_e32 v186, v108, v228
	v_mul_f32_e32 v187, v109, v229
	v_rndne_f32_e32 v186, v186
	v_rndne_f32_e32 v187, v187
	v_cvt_i32_f32_sdwa v190, v186 dst_sel:BYTE_1 dst_unused:UNUSED_PRESERVE src0_sel:DWORD
	v_cvt_i32_f32_sdwa v196, v187 dst_sel:BYTE_1 dst_unused:UNUSED_PRESERVE src0_sel:DWORD
	v_mul_f32_e32 v186, v112, v228
	v_mul_f32_e32 v187, v113, v229
	v_rndne_f32_e32 v186, v186
	v_rndne_f32_e32 v187, v187
	v_cvt_i32_f32_sdwa v190, v186 dst_sel:BYTE_2 dst_unused:UNUSED_PRESERVE src0_sel:DWORD
	v_cvt_i32_f32_sdwa v196, v187 dst_sel:BYTE_2 dst_unused:UNUSED_PRESERVE src0_sel:DWORD
	v_mul_f32_e32 v186, v116, v228
	v_mul_f32_e32 v187, v117, v229
	v_rndne_f32_e32 v186, v186
	v_rndne_f32_e32 v187, v187
	v_cvt_i32_f32_sdwa v190, v186 dst_sel:BYTE_3 dst_unused:UNUSED_PRESERVE src0_sel:DWORD
	v_cvt_i32_f32_sdwa v196, v187 dst_sel:BYTE_3 dst_unused:UNUSED_PRESERVE src0_sel:DWORD
	s_nop 0
	ds_write_b32 v139, v190 offset:1408
	ds_write_b32 v139, v196 offset:1920
	s_cmp_ge_u32 s10, 0x560
	s_cbranch_scc1 .Lc16_ffn1_nopf_6
	global_load_dwordx4 v[102:105], v138, s[56:57]
	s_add_u32 s56, s56, 0x15800
	s_addc_u32 s57, s57, 0
	global_load_dwordx4 v[106:109], v138, s[56:57]
	s_add_u32 s56, s56, 0x15800
	s_addc_u32 s57, s57, 0
	global_load_dwordx4 v[110:113], v138, s[56:57]
	s_add_u32 s56, s56, 0x15800
	s_addc_u32 s57, s57, 0
	global_load_dwordx4 v[114:117], v138, s[56:57]
	s_add_u32 s56, s56, 0x51f800
	s_addc_u32 s57, s57, 0
.Lc16_ffn1_nopf_6:
	v_mul_f32_e32 v186, v118, v226
	v_mul_f32_e32 v187, v119, v227
	v_rndne_f32_e32 v186, v186
	v_rndne_f32_e32 v187, v187
	v_cvt_i32_f32_sdwa v190, v186 dst_sel:BYTE_0 dst_unused:UNUSED_PAD src0_sel:DWORD
	v_cvt_i32_f32_sdwa v196, v187 dst_sel:BYTE_0 dst_unused:UNUSED_PAD src0_sel:DWORD
	v_mul_f32_e32 v186, v122, v226
	v_mul_f32_e32 v187, v123, v227
	v_rndne_f32_e32 v186, v186
	v_rndne_f32_e32 v187, v187
	v_cvt_i32_f32_sdwa v190, v186 dst_sel:BYTE_1 dst_unused:UNUSED_PRESERVE src0_sel:DWORD
	v_cvt_i32_f32_sdwa v196, v187 dst_sel:BYTE_1 dst_unused:UNUSED_PRESERVE src0_sel:DWORD
	v_mul_f32_e32 v186, v126, v226
	v_mul_f32_e32 v187, v127, v227
	v_rndne_f32_e32 v186, v186
	v_rndne_f32_e32 v187, v187
	v_cvt_i32_f32_sdwa v190, v186 dst_sel:BYTE_2 dst_unused:UNUSED_PRESERVE src0_sel:DWORD
	v_cvt_i32_f32_sdwa v196, v187 dst_sel:BYTE_2 dst_unused:UNUSED_PRESERVE src0_sel:DWORD
	v_mul_f32_e32 v186, v130, v226
	v_mul_f32_e32 v187, v131, v227
	v_rndne_f32_e32 v186, v186
	v_rndne_f32_e32 v187, v187
	v_cvt_i32_f32_sdwa v190, v186 dst_sel:BYTE_3 dst_unused:UNUSED_PRESERVE src0_sel:DWORD
	v_cvt_i32_f32_sdwa v196, v187 dst_sel:BYTE_3 dst_unused:UNUSED_PRESERVE src0_sel:DWORD
	s_nop 0
	ds_write_b32 v139, v190 offset:448
	ds_write_b32 v139, v196 offset:960
	v_mul_f32_e32 v186, v120, v228
	v_mul_f32_e32 v187, v121, v229
	v_rndne_f32_e32 v186, v186
	v_rndne_f32_e32 v187, v187
	v_cvt_i32_f32_sdwa v190, v186 dst_sel:BYTE_0 dst_unused:UNUSED_PAD src0_sel:DWORD
	v_cvt_i32_f32_sdwa v196, v187 dst_sel:BYTE_0 dst_unused:UNUSED_PAD src0_sel:DWORD
	v_mul_f32_e32 v186, v124, v228
	v_mul_f32_e32 v187, v125, v229
	v_rndne_f32_e32 v186, v186
	v_rndne_f32_e32 v187, v187
	v_cvt_i32_f32_sdwa v190, v186 dst_sel:BYTE_1 dst_unused:UNUSED_PRESERVE src0_sel:DWORD
	v_cvt_i32_f32_sdwa v196, v187 dst_sel:BYTE_1 dst_unused:UNUSED_PRESERVE src0_sel:DWORD
	v_mul_f32_e32 v186, v128, v228
	v_mul_f32_e32 v187, v129, v229
	v_rndne_f32_e32 v186, v186
	v_rndne_f32_e32 v187, v187
	v_cvt_i32_f32_sdwa v190, v186 dst_sel:BYTE_2 dst_unused:UNUSED_PRESERVE src0_sel:DWORD
	v_cvt_i32_f32_sdwa v196, v187 dst_sel:BYTE_2 dst_unused:UNUSED_PRESERVE src0_sel:DWORD
	v_mul_f32_e32 v186, v132, v228
	v_mul_f32_e32 v187, v133, v229
	v_rndne_f32_e32 v186, v186
	v_rndne_f32_e32 v187, v187
	v_cvt_i32_f32_sdwa v190, v186 dst_sel:BYTE_3 dst_unused:UNUSED_PRESERVE src0_sel:DWORD
	v_cvt_i32_f32_sdwa v196, v187 dst_sel:BYTE_3 dst_unused:UNUSED_PRESERVE src0_sel:DWORD
	s_nop 0
	ds_write_b32 v139, v190 offset:1472
	ds_write_b32 v139, v196 offset:1984
	s_cmp_ge_u32 s10, 0x560
	s_cbranch_scc1 .Lc16_ffn1_nopf_7
	global_load_dwordx4 v[118:121], v138, s[56:57]
	s_add_u32 s56, s56, 0x15800
	s_addc_u32 s57, s57, 0
	global_load_dwordx4 v[122:125], v138, s[56:57]
	s_add_u32 s56, s56, 0x15800
	s_addc_u32 s57, s57, 0
	global_load_dwordx4 v[126:129], v138, s[56:57]
	s_add_u32 s56, s56, 0x15800
	s_addc_u32 s57, s57, 0
	global_load_dwordx4 v[130:133], v138, s[56:57]

.Lc16_mixer_nobf_0:
	v_mul_f32_e32 v186, v6, v226
	v_mul_f32_e32 v187, v7, v227
	v_rndne_f32_e32 v186, v186
	v_rndne_f32_e32 v187, v187
	v_cvt_i32_f32_sdwa v190, v186 dst_sel:BYTE_0 dst_unused:UNUSED_PAD src0_sel:DWORD
	v_cvt_i32_f32_sdwa v196, v187 dst_sel:BYTE_0 dst_unused:UNUSED_PAD src0_sel:DWORD
	v_mul_f32_e32 v186, v10, v226
	v_mul_f32_e32 v187, v11, v227
	v_rndne_f32_e32 v186, v186
	v_rndne_f32_e32 v187, v187
	v_cvt_i32_f32_sdwa v190, v186 dst_sel:BYTE_1 dst_unused:UNUSED_PRESERVE src0_sel:DWORD
	v_cvt_i32_f32_sdwa v196, v187 dst_sel:BYTE_1 dst_unused:UNUSED_PRESERVE src0_sel:DWORD
	v_mul_f32_e32 v186, v14, v226
	v_mul_f32_e32 v187, v15, v227
	v_rndne_f32_e32 v186, v186
	v_rndne_f32_e32 v187, v187
	v_cvt_i32_f32_sdwa v190, v186 dst_sel:BYTE_2 dst_unused:UNUSED_PRESERVE src0_sel:DWORD
	v_cvt_i32_f32_sdwa v196, v187 dst_sel:BYTE_2 dst_unused:UNUSED_PRESERVE src0_sel:DWORD
	v_mul_f32_e32 v186, v18, v226
	v_mul_f32_e32 v187, v19, v227
	v_rndne_f32_e32 v186, v186
	v_rndne_f32_e32 v187, v187
	v_cvt_i32_f32_sdwa v190, v186 dst_sel:BYTE_3 dst_unused:UNUSED_PRESERVE src0_sel:DWORD
	v_cvt_i32_f32_sdwa v196, v187 dst_sel:BYTE_3 dst_unused:UNUSED_PRESERVE src0_sel:DWORD
	s_nop 0
	ds_write_b32 v139, v190 offset:0
	ds_write_b32 v139, v196 offset:512
	v_mul_f32_e32 v186, v8, v228
	v_mul_f32_e32 v187, v9, v229
	v_rndne_f32_e32 v186, v186
	v_rndne_f32_e32 v187, v187
	v_cvt_i32_f32_sdwa v190, v186 dst_sel:BYTE_0 dst_unused:UNUSED_PAD src0_sel:DWORD
	v_cvt_i32_f32_sdwa v196, v187 dst_sel:BYTE_0 dst_unused:UNUSED_PAD src0_sel:DWORD
	v_mul_f32_e32 v186, v12, v228
	v_mul_f32_e32 v187, v13, v229
	v_rndne_f32_e32 v186, v186
	v_rndne_f32_e32 v187, v187
	v_cvt_i32_f32_sdwa v190, v186 dst_sel:BYTE_1 dst_unused:UNUSED_PRESERVE src0_sel:DWORD
	v_cvt_i32_f32_sdwa v196, v187 dst_sel:BYTE_1 dst_unused:UNUSED_PRESERVE src0_sel:DWORD
	v_mul_f32_e32 v186, v16, v228
	v_mul_f32_e32 v187, v17, v229
	v_rndne_f32_e32 v186, v186
	v_rndne_f32_e32 v187, v187
	v_cvt_i32_f32_sdwa v190, v186 dst_sel:BYTE_2 dst_unused:UNUSED_PRESERVE src0_sel:DWORD
	v_cvt_i32_f32_sdwa v196, v187 dst_sel:BYTE_2 dst_unused:UNUSED_PRESERVE src0_sel:DWORD
	v_mul_f32_e32 v186, v20, v228
	v_mul_f32_e32 v187, v21, v229
	v_rndne_f32_e32 v186, v186
	v_rndne_f32_e32 v187, v187
	v_cvt_i32_f32_sdwa v190, v186 dst_sel:BYTE_3 dst_unused:UNUSED_PRESERVE src0_sel:DWORD
	v_cvt_i32_f32_sdwa v196, v187 dst_sel:BYTE_3 dst_unused:UNUSED_PRESERVE src0_sel:DWORD
	s_nop 0
	ds_write_b32 v139, v190 offset:1024
	ds_write_b32 v139, v196 offset:1536
	s_cmp_ge_u32 s10, 0x280
	s_cbranch_scc1 .Lc16_mixer_nopf_0
	global_load_dwordx4 v[6:9], v138, s[56:57]
	s_add_u32 s56, s56, 0xa000
	s_addc_u32 s57, s57, 0
	global_load_dwordx4 v[10:13], v138, s[56:57]
	s_add_u32 s56, s56, 0xa000
	s_addc_u32 s57, s57, 0
	global_load_dwordx4 v[14:17], v138, s[56:57]
	s_add_u32 s56, s56, 0xa000
	s_addc_u32 s57, s57, 0
	global_load_dwordx4 v[18:21], v138, s[56:57]
	s_add_u32 s56, s56, 0x262000
	s_addc_u32 s57, s57, 0

.Lc16_mixer_nobf_1:
	v_mul_f32_e32 v186, v22, v226
	v_mul_f32_e32 v187, v23, v227
	v_rndne_f32_e32 v186, v186
	v_rndne_f32_e32 v187, v187
	v_cvt_i32_f32_sdwa v190, v186 dst_sel:BYTE_0 dst_unused:UNUSED_PAD src0_sel:DWORD
	v_cvt_i32_f32_sdwa v196, v187 dst_sel:BYTE_0 dst_unused:UNUSED_PAD src0_sel:DWORD
	v_mul_f32_e32 v186, v26, v226
	v_mul_f32_e32 v187, v27, v227
	v_rndne_f32_e32 v186, v186
	v_rndne_f32_e32 v187, v187
	v_cvt_i32_f32_sdwa v190, v186 dst_sel:BYTE_1 dst_unused:UNUSED_PRESERVE src0_sel:DWORD
	v_cvt_i32_f32_sdwa v196, v187 dst_sel:BYTE_1 dst_unused:UNUSED_PRESERVE src0_sel:DWORD
	v_mul_f32_e32 v186, v30, v226
	v_mul_f32_e32 v187, v31, v227
	v_rndne_f32_e32 v186, v186
	v_rndne_f32_e32 v187, v187
	v_cvt_i32_f32_sdwa v190, v186 dst_sel:BYTE_2 dst_unused:UNUSED_PRESERVE src0_sel:DWORD
	v_cvt_i32_f32_sdwa v196, v187 dst_sel:BYTE_2 dst_unused:UNUSED_PRESERVE src0_sel:DWORD
	v_mul_f32_e32 v186, v34, v226
	v_mul_f32_e32 v187, v35, v227
	v_rndne_f32_e32 v186, v186
	v_rndne_f32_e32 v187, v187
	v_cvt_i32_f32_sdwa v190, v186 dst_sel:BYTE_3 dst_unused:UNUSED_PRESERVE src0_sel:DWORD
	v_cvt_i32_f32_sdwa v196, v187 dst_sel:BYTE_3 dst_unused:UNUSED_PRESERVE src0_sel:DWORD
	s_nop 0
	ds_write_b32 v139, v190 offset:64
	ds_write_b32 v139, v196 offset:576
	v_mul_f32_e32 v186, v24, v228
	v_mul_f32_e32 v187, v25, v229
	v_rndne_f32_e32 v186, v186
	v_rndne_f32_e32 v187, v187
	v_cvt_i32_f32_sdwa v190, v186 dst_sel:BYTE_0 dst_unused:UNUSED_PAD src0_sel:DWORD
	v_cvt_i32_f32_sdwa v196, v187 dst_sel:BYTE_0 dst_unused:UNUSED_PAD src0_sel:DWORD
	v_mul_f32_e32 v186, v28, v228
	v_mul_f32_e32 v187, v29, v229
	v_rndne_f32_e32 v186, v186
	v_rndne_f32_e32 v187, v187
	v_cvt_i32_f32_sdwa v190, v186 dst_sel:BYTE_1 dst_unused:UNUSED_PRESERVE src0_sel:DWORD
	v_cvt_i32_f32_sdwa v196, v187 dst_sel:BYTE_1 dst_unused:UNUSED_PRESERVE src0_sel:DWORD
	v_mul_f32_e32 v186, v32, v228
	v_mul_f32_e32 v187, v33, v229
	v_rndne_f32_e32 v186, v186
	v_rndne_f32_e32 v187, v187
	v_cvt_i32_f32_sdwa v190, v186 dst_sel:BYTE_2 dst_unused:UNUSED_PRESERVE src0_sel:DWORD
	v_cvt_i32_f32_sdwa v196, v187 dst_sel:BYTE_2 dst_unused:UNUSED_PRESERVE src0_sel:DWORD
	v_mul_f32_e32 v186, v36, v228
	v_mul_f32_e32 v187, v37, v229
	v_rndne_f32_e32 v186, v186
	v_rndne_f32_e32 v187, v187
	v_cvt_i32_f32_sdwa v190, v186 dst_sel:BYTE_3 dst_unused:UNUSED_PRESERVE src0_sel:DWORD
	v_cvt_i32_f32_sdwa v196, v187 dst_sel:BYTE_3 dst_unused:UNUSED_PRESERVE src0_sel:DWORD
	s_nop 0
	ds_write_b32 v139, v190 offset:1088
	ds_write_b32 v139, v196 offset:1600
	s_cmp_ge_u32 s10, 0x280
	s_cbranch_scc1 .Lc16_mixer_nopf_1
	global_load_dwordx4 v[22:25], v138, s[56:57]
	s_add_u32 s56, s56, 0xa000
	s_addc_u32 s57, s57, 0
	global_load_dwordx4 v[26:29], v138, s[56:57]
	s_add_u32 s56, s56, 0xa000
	s_addc_u32 s57, s57, 0
	global_load_dwordx4 v[30:33], v138, s[56:57]
	s_add_u32 s56, s56, 0xa000
	s_addc_u32 s57, s57, 0
	global_load_dwordx4 v[34:37], v138, s[56:57]
	s_add_u32 s56, s56, 0x262000
	s_addc_u32 s57, s57, 0

.Lc16_mixer_nobf_2:
	v_mul_f32_e32 v186, v38, v226
	v_mul_f32_e32 v187, v39, v227
	v_rndne_f32_e32 v186, v186
	v_rndne_f32_e32 v187, v187
	v_cvt_i32_f32_sdwa v190, v186 dst_sel:BYTE_0 dst_unused:UNUSED_PAD src0_sel:DWORD
	v_cvt_i32_f32_sdwa v196, v187 dst_sel:BYTE_0 dst_unused:UNUSED_PAD src0_sel:DWORD
	v_mul_f32_e32 v186, v42, v226
	v_mul_f32_e32 v187, v43, v227
	v_rndne_f32_e32 v186, v186
	v_rndne_f32_e32 v187, v187
	v_cvt_i32_f32_sdwa v190, v186 dst_sel:BYTE_1 dst_unused:UNUSED_PRESERVE src0_sel:DWORD
	v_cvt_i32_f32_sdwa v196, v187 dst_sel:BYTE_1 dst_unused:UNUSED_PRESERVE src0_sel:DWORD
	v_mul_f32_e32 v186, v46, v226
	v_mul_f32_e32 v187, v47, v227
	v_rndne_f32_e32 v186, v186
	v_rndne_f32_e32 v187, v187
	v_cvt_i32_f32_sdwa v190, v186 dst_sel:BYTE_2 dst_unused:UNUSED_PRESERVE src0_sel:DWORD
	v_cvt_i32_f32_sdwa v196, v187 dst_sel:BYTE_2 dst_unused:UNUSED_PRESERVE src0_sel:DWORD
	v_mul_f32_e32 v186, v50, v226
	v_mul_f32_e32 v187, v51, v227
	v_rndne_f32_e32 v186, v186
	v_rndne_f32_e32 v187, v187
	v_cvt_i32_f32_sdwa v190, v186 dst_sel:BYTE_3 dst_unused:UNUSED_PRESERVE src0_sel:DWORD
	v_cvt_i32_f32_sdwa v196, v187 dst_sel:BYTE_3 dst_unused:UNUSED_PRESERVE src0_sel:DWORD
	s_nop 0
	ds_write_b32 v139, v190 offset:128
	ds_write_b32 v139, v196 offset:640
	v_mul_f32_e32 v186, v40, v228
	v_mul_f32_e32 v187, v41, v229
	v_rndne_f32_e32 v186, v186
	v_rndne_f32_e32 v187, v187
	v_cvt_i32_f32_sdwa v190, v186 dst_sel:BYTE_0 dst_unused:UNUSED_PAD src0_sel:DWORD
	v_cvt_i32_f32_sdwa v196, v187 dst_sel:BYTE_0 dst_unused:UNUSED_PAD src0_sel:DWORD
	v_mul_f32_e32 v186, v44, v228
	v_mul_f32_e32 v187, v45, v229
	v_rndne_f32_e32 v186, v186
	v_rndne_f32_e32 v187, v187
	v_cvt_i32_f32_sdwa v190, v186 dst_sel:BYTE_1 dst_unused:UNUSED_PRESERVE src0_sel:DWORD
	v_cvt_i32_f32_sdwa v196, v187 dst_sel:BYTE_1 dst_unused:UNUSED_PRESERVE src0_sel:DWORD
	v_mul_f32_e32 v186, v48, v228
	v_mul_f32_e32 v187, v49, v229
	v_rndne_f32_e32 v186, v186
	v_rndne_f32_e32 v187, v187
	v_cvt_i32_f32_sdwa v190, v186 dst_sel:BYTE_2 dst_unused:UNUSED_PRESERVE src0_sel:DWORD
	v_cvt_i32_f32_sdwa v196, v187 dst_sel:BYTE_2 dst_unused:UNUSED_PRESERVE src0_sel:DWORD
	v_mul_f32_e32 v186, v52, v228
	v_mul_f32_e32 v187, v53, v229
	v_rndne_f32_e32 v186, v186
	v_rndne_f32_e32 v187, v187
	v_cvt_i32_f32_sdwa v190, v186 dst_sel:BYTE_3 dst_unused:UNUSED_PRESERVE src0_sel:DWORD
	v_cvt_i32_f32_sdwa v196, v187 dst_sel:BYTE_3 dst_unused:UNUSED_PRESERVE src0_sel:DWORD
	s_nop 0
	ds_write_b32 v139, v190 offset:1152
	ds_write_b32 v139, v196 offset:1664
	s_cmp_ge_u32 s10, 0x280
	s_cbranch_scc1 .Lc16_mixer_nopf_2
	global_load_dwordx4 v[38:41], v138, s[56:57]
	s_add_u32 s56, s56, 0xa000
	s_addc_u32 s57, s57, 0
	global_load_dwordx4 v[42:45], v138, s[56:57]
	s_add_u32 s56, s56, 0xa000
	s_addc_u32 s57, s57, 0
	global_load_dwordx4 v[46:49], v138, s[56:57]
	s_add_u32 s56, s56, 0xa000
	s_addc_u32 s57, s57, 0
	global_load_dwordx4 v[50:53], v138, s[56:57]
	s_add_u32 s56, s56, 0x262000
	s_addc_u32 s57, s57, 0

.Lc16_mixer_nobf_3:
	v_mul_f32_e32 v186, v54, v226
	v_mul_f32_e32 v187, v55, v227
	v_rndne_f32_e32 v186, v186
	v_rndne_f32_e32 v187, v187
	v_cvt_i32_f32_sdwa v190, v186 dst_sel:BYTE_0 dst_unused:UNUSED_PAD src0_sel:DWORD
	v_cvt_i32_f32_sdwa v196, v187 dst_sel:BYTE_0 dst_unused:UNUSED_PAD src0_sel:DWORD
	v_mul_f32_e32 v186, v58, v226
	v_mul_f32_e32 v187, v59, v227
	v_rndne_f32_e32 v186, v186
	v_rndne_f32_e32 v187, v187
	v_cvt_i32_f32_sdwa v190, v186 dst_sel:BYTE_1 dst_unused:UNUSED_PRESERVE src0_sel:DWORD
	v_cvt_i32_f32_sdwa v196, v187 dst_sel:BYTE_1 dst_unused:UNUSED_PRESERVE src0_sel:DWORD
	v_mul_f32_e32 v186, v62, v226
	v_mul_f32_e32 v187, v63, v227
	v_rndne_f32_e32 v186, v186
	v_rndne_f32_e32 v187, v187
	v_cvt_i32_f32_sdwa v190, v186 dst_sel:BYTE_2 dst_unused:UNUSED_PRESERVE src0_sel:DWORD
	v_cvt_i32_f32_sdwa v196, v187 dst_sel:BYTE_2 dst_unused:UNUSED_PRESERVE src0_sel:DWORD
	v_mul_f32_e32 v186, v66, v226
	v_mul_f32_e32 v187, v67, v227
	v_rndne_f32_e32 v186, v186
	v_rndne_f32_e32 v187, v187
	v_cvt_i32_f32_sdwa v190, v186 dst_sel:BYTE_3 dst_unused:UNUSED_PRESERVE src0_sel:DWORD
	v_cvt_i32_f32_sdwa v196, v187 dst_sel:BYTE_3 dst_unused:UNUSED_PRESERVE src0_sel:DWORD
	s_nop 0
	ds_write_b32 v139, v190 offset:192
	ds_write_b32 v139, v196 offset:704
	v_mul_f32_e32 v186, v56, v228
	v_mul_f32_e32 v187, v57, v229
	v_rndne_f32_e32 v186, v186
	v_rndne_f32_e32 v187, v187
	v_cvt_i32_f32_sdwa v190, v186 dst_sel:BYTE_0 dst_unused:UNUSED_PAD src0_sel:DWORD
	v_cvt_i32_f32_sdwa v196, v187 dst_sel:BYTE_0 dst_unused:UNUSED_PAD src0_sel:DWORD
	v_mul_f32_e32 v186, v60, v228
	v_mul_f32_e32 v187, v61, v229
	v_rndne_f32_e32 v186, v186
	v_rndne_f32_e32 v187, v187
	v_cvt_i32_f32_sdwa v190, v186 dst_sel:BYTE_1 dst_unused:UNUSED_PRESERVE src0_sel:DWORD
	v_cvt_i32_f32_sdwa v196, v187 dst_sel:BYTE_1 dst_unused:UNUSED_PRESERVE src0_sel:DWORD
	v_mul_f32_e32 v186, v64, v228
	v_mul_f32_e32 v187, v65, v229
	v_rndne_f32_e32 v186, v186
	v_rndne_f32_e32 v187, v187
	v_cvt_i32_f32_sdwa v190, v186 dst_sel:BYTE_2 dst_unused:UNUSED_PRESERVE src0_sel:DWORD
	v_cvt_i32_f32_sdwa v196, v187 dst_sel:BYTE_2 dst_unused:UNUSED_PRESERVE src0_sel:DWORD
	v_mul_f32_e32 v186, v68, v228
	v_mul_f32_e32 v187, v69, v229
	v_rndne_f32_e32 v186, v186
	v_rndne_f32_e32 v187, v187
	v_cvt_i32_f32_sdwa v190, v186 dst_sel:BYTE_3 dst_unused:UNUSED_PRESERVE src0_sel:DWORD
	v_cvt_i32_f32_sdwa v196, v187 dst_sel:BYTE_3 dst_unused:UNUSED_PRESERVE src0_sel:DWORD
	s_nop 0
	ds_write_b32 v139, v190 offset:1216
	ds_write_b32 v139, v196 offset:1728
	s_cmp_ge_u32 s10, 0x280
	s_cbranch_scc1 .Lc16_mixer_nopf_3
	global_load_dwordx4 v[54:57], v138, s[56:57]
	s_add_u32 s56, s56, 0xa000
	s_addc_u32 s57, s57, 0
	global_load_dwordx4 v[58:61], v138, s[56:57]
	s_add_u32 s56, s56, 0xa000
	s_addc_u32 s57, s57, 0
	global_load_dwordx4 v[62:65], v138, s[56:57]
	s_add_u32 s56, s56, 0xa000
	s_addc_u32 s57, s57, 0
	global_load_dwordx4 v[66:69], v138, s[56:57]
	s_add_u32 s56, s56, 0x262000
	s_addc_u32 s57, s57, 0

.Lc16_mixer_nobf_4:
	v_mul_f32_e32 v186, v70, v226
	v_mul_f32_e32 v187, v71, v227
	v_rndne_f32_e32 v186, v186
	v_rndne_f32_e32 v187, v187
	v_cvt_i32_f32_sdwa v190, v186 dst_sel:BYTE_0 dst_unused:UNUSED_PAD src0_sel:DWORD
	v_cvt_i32_f32_sdwa v196, v187 dst_sel:BYTE_0 dst_unused:UNUSED_PAD src0_sel:DWORD
	v_mul_f32_e32 v186, v74, v226
	v_mul_f32_e32 v187, v75, v227
	v_rndne_f32_e32 v186, v186
	v_rndne_f32_e32 v187, v187
	v_cvt_i32_f32_sdwa v190, v186 dst_sel:BYTE_1 dst_unused:UNUSED_PRESERVE src0_sel:DWORD
	v_cvt_i32_f32_sdwa v196, v187 dst_sel:BYTE_1 dst_unused:UNUSED_PRESERVE src0_sel:DWORD
	v_mul_f32_e32 v186, v78, v226
	v_mul_f32_e32 v187, v79, v227
	v_rndne_f32_e32 v186, v186
	v_rndne_f32_e32 v187, v187
	v_cvt_i32_f32_sdwa v190, v186 dst_sel:BYTE_2 dst_unused:UNUSED_PRESERVE src0_sel:DWORD
	v_cvt_i32_f32_sdwa v196, v187 dst_sel:BYTE_2 dst_unused:UNUSED_PRESERVE src0_sel:DWORD
	v_mul_f32_e32 v186, v82, v226
	v_mul_f32_e32 v187, v83, v227
	v_rndne_f32_e32 v186, v186
	v_rndne_f32_e32 v187, v187
	v_cvt_i32_f32_sdwa v190, v186 dst_sel:BYTE_3 dst_unused:UNUSED_PRESERVE src0_sel:DWORD
	v_cvt_i32_f32_sdwa v196, v187 dst_sel:BYTE_3 dst_unused:UNUSED_PRESERVE src0_sel:DWORD
	s_nop 0
	ds_write_b32 v139, v190 offset:256
	ds_write_b32 v139, v196 offset:768
	v_mul_f32_e32 v186, v72, v228
	v_mul_f32_e32 v187, v73, v229
	v_rndne_f32_e32 v186, v186
	v_rndne_f32_e32 v187, v187
	v_cvt_i32_f32_sdwa v190, v186 dst_sel:BYTE_0 dst_unused:UNUSED_PAD src0_sel:DWORD
	v_cvt_i32_f32_sdwa v196, v187 dst_sel:BYTE_0 dst_unused:UNUSED_PAD src0_sel:DWORD
	v_mul_f32_e32 v186, v76, v228
	v_mul_f32_e32 v187, v77, v229
	v_rndne_f32_e32 v186, v186
	v_rndne_f32_e32 v187, v187
	v_cvt_i32_f32_sdwa v190, v186 dst_sel:BYTE_1 dst_unused:UNUSED_PRESERVE src0_sel:DWORD
	v_cvt_i32_f32_sdwa v196, v187 dst_sel:BYTE_1 dst_unused:UNUSED_PRESERVE src0_sel:DWORD
	v_mul_f32_e32 v186, v80, v228
	v_mul_f32_e32 v187, v81, v229
	v_rndne_f32_e32 v186, v186
	v_rndne_f32_e32 v187, v187
	v_cvt_i32_f32_sdwa v190, v186 dst_sel:BYTE_2 dst_unused:UNUSED_PRESERVE src0_sel:DWORD
	v_cvt_i32_f32_sdwa v196, v187 dst_sel:BYTE_2 dst_unused:UNUSED_PRESERVE src0_sel:DWORD
	v_mul_f32_e32 v186, v84, v228
	v_mul_f32_e32 v187, v85, v229
	v_rndne_f32_e32 v186, v186
	v_rndne_f32_e32 v187, v187
	v_cvt_i32_f32_sdwa v190, v186 dst_sel:BYTE_3 dst_unused:UNUSED_PRESERVE src0_sel:DWORD
	v_cvt_i32_f32_sdwa v196, v187 dst_sel:BYTE_3 dst_unused:UNUSED_PRESERVE src0_sel:DWORD
	s_nop 0
	ds_write_b32 v139, v190 offset:1280
	ds_write_b32 v139, v196 offset:1792
	s_cmp_ge_u32 s10, 0x280
	s_cbranch_scc1 .Lc16_mixer_nopf_4
	global_load_dwordx4 v[70:73], v138, s[56:57]
	s_add_u32 s56, s56, 0xa000
	s_addc_u32 s57, s57, 0
	global_load_dwordx4 v[74:77], v138, s[56:57]
	s_add_u32 s56, s56, 0xa000
	s_addc_u32 s57, s57, 0
	global_load_dwordx4 v[78:81], v138, s[56:57]
	s_add_u32 s56, s56, 0xa000
	s_addc_u32 s57, s57, 0
	global_load_dwordx4 v[82:85], v138, s[56:57]
	s_add_u32 s56, s56, 0x262000
	s_addc_u32 s57, s57, 0

.Lc16_mixer_nobf_5:
	v_mul_f32_e32 v186, v86, v226
	v_mul_f32_e32 v187, v87, v227
	v_rndne_f32_e32 v186, v186
	v_rndne_f32_e32 v187, v187
	v_cvt_i32_f32_sdwa v190, v186 dst_sel:BYTE_0 dst_unused:UNUSED_PAD src0_sel:DWORD
	v_cvt_i32_f32_sdwa v196, v187 dst_sel:BYTE_0 dst_unused:UNUSED_PAD src0_sel:DWORD
	v_mul_f32_e32 v186, v90, v226
	v_mul_f32_e32 v187, v91, v227
	v_rndne_f32_e32 v186, v186
	v_rndne_f32_e32 v187, v187
	v_cvt_i32_f32_sdwa v190, v186 dst_sel:BYTE_1 dst_unused:UNUSED_PRESERVE src0_sel:DWORD
	v_cvt_i32_f32_sdwa v196, v187 dst_sel:BYTE_1 dst_unused:UNUSED_PRESERVE src0_sel:DWORD
	v_mul_f32_e32 v186, v94, v226
	v_mul_f32_e32 v187, v95, v227
	v_rndne_f32_e32 v186, v186
	v_rndne_f32_e32 v187, v187
	v_cvt_i32_f32_sdwa v190, v186 dst_sel:BYTE_2 dst_unused:UNUSED_PRESERVE src0_sel:DWORD
	v_cvt_i32_f32_sdwa v196, v187 dst_sel:BYTE_2 dst_unused:UNUSED_PRESERVE src0_sel:DWORD
	v_mul_f32_e32 v186, v98, v226
	v_mul_f32_e32 v187, v99, v227
	v_rndne_f32_e32 v186, v186
	v_rndne_f32_e32 v187, v187
	v_cvt_i32_f32_sdwa v190, v186 dst_sel:BYTE_3 dst_unused:UNUSED_PRESERVE src0_sel:DWORD
	v_cvt_i32_f32_sdwa v196, v187 dst_sel:BYTE_3 dst_unused:UNUSED_PRESERVE src0_sel:DWORD
	s_nop 0
	ds_write_b32 v139, v190 offset:320
	ds_write_b32 v139, v196 offset:832
	v_mul_f32_e32 v186, v88, v228
	v_mul_f32_e32 v187, v89, v229
	v_rndne_f32_e32 v186, v186
	v_rndne_f32_e32 v187, v187
	v_cvt_i32_f32_sdwa v190, v186 dst_sel:BYTE_0 dst_unused:UNUSED_PAD src0_sel:DWORD
	v_cvt_i32_f32_sdwa v196, v187 dst_sel:BYTE_0 dst_unused:UNUSED_PAD src0_sel:DWORD
	v_mul_f32_e32 v186, v92, v228
	v_mul_f32_e32 v187, v93, v229
	v_rndne_f32_e32 v186, v186
	v_rndne_f32_e32 v187, v187
	v_cvt_i32_f32_sdwa v190, v186 dst_sel:BYTE_1 dst_unused:UNUSED_PRESERVE src0_sel:DWORD
	v_cvt_i32_f32_sdwa v196, v187 dst_sel:BYTE_1 dst_unused:UNUSED_PRESERVE src0_sel:DWORD
	v_mul_f32_e32 v186, v96, v228
	v_mul_f32_e32 v187, v97, v229
	v_rndne_f32_e32 v186, v186
	v_rndne_f32_e32 v187, v187
	v_cvt_i32_f32_sdwa v190, v186 dst_sel:BYTE_2 dst_unused:UNUSED_PRESERVE src0_sel:DWORD
	v_cvt_i32_f32_sdwa v196, v187 dst_sel:BYTE_2 dst_unused:UNUSED_PRESERVE src0_sel:DWORD
	v_mul_f32_e32 v186, v100, v228
	v_mul_f32_e32 v187, v101, v229
	v_rndne_f32_e32 v186, v186
	v_rndne_f32_e32 v187, v187
	v_cvt_i32_f32_sdwa v190, v186 dst_sel:BYTE_3 dst_unused:UNUSED_PRESERVE src0_sel:DWORD
	v_cvt_i32_f32_sdwa v196, v187 dst_sel:BYTE_3 dst_unused:UNUSED_PRESERVE src0_sel:DWORD
	s_nop 0
	ds_write_b32 v139, v190 offset:1344
	ds_write_b32 v139, v196 offset:1856
	s_cmp_ge_u32 s10, 0x280
	s_cbranch_scc1 .Lc16_mixer_nopf_5
	global_load_dwordx4 v[86:89], v138, s[56:57]
	s_add_u32 s56, s56, 0xa000
	s_addc_u32 s57, s57, 0
	global_load_dwordx4 v[90:93], v138, s[56:57]
	s_add_u32 s56, s56, 0xa000
	s_addc_u32 s57, s57, 0
	global_load_dwordx4 v[94:97], v138, s[56:57]
	s_add_u32 s56, s56, 0xa000
	s_addc_u32 s57, s57, 0
	global_load_dwordx4 v[98:101], v138, s[56:57]
	s_add_u32 s56, s56, 0x262000
	s_addc_u32 s57, s57, 0

.Lc16_mixer_nobf_6:
	v_mul_f32_e32 v186, v102, v226
	v_mul_f32_e32 v187, v103, v227
	v_rndne_f32_e32 v186, v186
	v_rndne_f32_e32 v187, v187
	v_cvt_i32_f32_sdwa v190, v186 dst_sel:BYTE_0 dst_unused:UNUSED_PAD src0_sel:DWORD
	v_cvt_i32_f32_sdwa v196, v187 dst_sel:BYTE_0 dst_unused:UNUSED_PAD src0_sel:DWORD
	v_mul_f32_e32 v186, v106, v226
	v_mul_f32_e32 v187, v107, v227
	v_rndne_f32_e32 v186, v186
	v_rndne_f32_e32 v187, v187
	v_cvt_i32_f32_sdwa v190, v186 dst_sel:BYTE_1 dst_unused:UNUSED_PRESERVE src0_sel:DWORD
	v_cvt_i32_f32_sdwa v196, v187 dst_sel:BYTE_1 dst_unused:UNUSED_PRESERVE src0_sel:DWORD
	v_mul_f32_e32 v186, v110, v226
	v_mul_f32_e32 v187, v111, v227
	v_rndne_f32_e32 v186, v186
	v_rndne_f32_e32 v187, v187
	v_cvt_i32_f32_sdwa v190, v186 dst_sel:BYTE_2 dst_unused:UNUSED_PRESERVE src0_sel:DWORD
	v_cvt_i32_f32_sdwa v196, v187 dst_sel:BYTE_2 dst_unused:UNUSED_PRESERVE src0_sel:DWORD
	v_mul_f32_e32 v186, v114, v226
	v_mul_f32_e32 v187, v115, v227
	v_rndne_f32_e32 v186, v186
	v_rndne_f32_e32 v187, v187
	v_cvt_i32_f32_sdwa v190, v186 dst_sel:BYTE_3 dst_unused:UNUSED_PRESERVE src0_sel:DWORD
	v_cvt_i32_f32_sdwa v196, v187 dst_sel:BYTE_3 dst_unused:UNUSED_PRESERVE src0_sel:DWORD
	s_nop 0
	ds_write_b32 v139, v190 offset:384
	ds_write_b32 v139, v196 offset:896
	v_mul_f32_e32 v186, v104, v228
	v_mul_f32_e32 v187, v105, v229
	v_rndne_f32_e32 v186, v186
	v_rndne_f32_e32 v187, v187
	v_cvt_i32_f32_sdwa v190, v186 dst_sel:BYTE_0 dst_unused:UNUSED_PAD src0_sel:DWORD
	v_cvt_i32_f32_sdwa v196, v187 dst_sel:BYTE_0 dst_unused:UNUSED_PAD src0_sel:DWORD
	v_mul_f32_e32 v186, v108, v228
	v_mul_f32_e32 v187, v109, v229
	v_rndne_f32_e32 v186, v186
	v_rndne_f32_e32 v187, v187
	v_cvt_i32_f32_sdwa v190, v186 dst_sel:BYTE_1 dst_unused:UNUSED_PRESERVE src0_sel:DWORD
	v_cvt_i32_f32_sdwa v196, v187 dst_sel:BYTE_1 dst_unused:UNUSED_PRESERVE src0_sel:DWORD
	v_mul_f32_e32 v186, v112, v228
	v_mul_f32_e32 v187, v113, v229
	v_rndne_f32_e32 v186, v186
	v_rndne_f32_e32 v187, v187
	v_cvt_i32_f32_sdwa v190, v186 dst_sel:BYTE_2 dst_unused:UNUSED_PRESERVE src0_sel:DWORD
	v_cvt_i32_f32_sdwa v196, v187 dst_sel:BYTE_2 dst_unused:UNUSED_PRESERVE src0_sel:DWORD
	v_mul_f32_e32 v186, v116, v228
	v_mul_f32_e32 v187, v117, v229
	v_rndne_f32_e32 v186, v186
	v_rndne_f32_e32 v187, v187
	v_cvt_i32_f32_sdwa v190, v186 dst_sel:BYTE_3 dst_unused:UNUSED_PRESERVE src0_sel:DWORD
	v_cvt_i32_f32_sdwa v196, v187 dst_sel:BYTE_3 dst_unused:UNUSED_PRESERVE src0_sel:DWORD
	s_nop 0
	ds_write_b32 v139, v190 offset:1408
	ds_write_b32 v139, v196 offset:1920
	s_cmp_ge_u32 s10, 0x280
	s_cbranch_scc1 .Lc16_mixer_nopf_6
	global_load_dwordx4 v[102:105], v138, s[56:57]
	s_add_u32 s56, s56, 0xa000
	s_addc_u32 s57, s57, 0
	global_load_dwordx4 v[106:109], v138, s[56:57]
	s_add_u32 s56, s56, 0xa000
	s_addc_u32 s57, s57, 0
	global_load_dwordx4 v[110:113], v138, s[56:57]
	s_add_u32 s56, s56, 0xa000
	s_addc_u32 s57, s57, 0
	global_load_dwordx4 v[114:117], v138, s[56:57]
	s_add_u32 s56, s56, 0x262000
	s_addc_u32 s57, s57, 0

.Lc16_mixer_nobf_7:
	v_mul_f32_e32 v186, v118, v226
	v_mul_f32_e32 v187, v119, v227
	v_rndne_f32_e32 v186, v186
	v_rndne_f32_e32 v187, v187
	v_cvt_i32_f32_sdwa v190, v186 dst_sel:BYTE_0 dst_unused:UNUSED_PAD src0_sel:DWORD
	v_cvt_i32_f32_sdwa v196, v187 dst_sel:BYTE_0 dst_unused:UNUSED_PAD src0_sel:DWORD
	v_mul_f32_e32 v186, v122, v226
	v_mul_f32_e32 v187, v123, v227
	v_rndne_f32_e32 v186, v186
	v_rndne_f32_e32 v187, v187
	v_cvt_i32_f32_sdwa v190, v186 dst_sel:BYTE_1 dst_unused:UNUSED_PRESERVE src0_sel:DWORD
	v_cvt_i32_f32_sdwa v196, v187 dst_sel:BYTE_1 dst_unused:UNUSED_PRESERVE src0_sel:DWORD
	v_mul_f32_e32 v186, v126, v226
	v_mul_f32_e32 v187, v127, v227
	v_rndne_f32_e32 v186, v186
	v_rndne_f32_e32 v187, v187
	v_cvt_i32_f32_sdwa v190, v186 dst_sel:BYTE_2 dst_unused:UNUSED_PRESERVE src0_sel:DWORD
	v_cvt_i32_f32_sdwa v196, v187 dst_sel:BYTE_2 dst_unused:UNUSED_PRESERVE src0_sel:DWORD
	v_mul_f32_e32 v186, v130, v226
	v_mul_f32_e32 v187, v131, v227
	v_rndne_f32_e32 v186, v186
	v_rndne_f32_e32 v187, v187
	v_cvt_i32_f32_sdwa v190, v186 dst_sel:BYTE_3 dst_unused:UNUSED_PRESERVE src0_sel:DWORD
	v_cvt_i32_f32_sdwa v196, v187 dst_sel:BYTE_3 dst_unused:UNUSED_PRESERVE src0_sel:DWORD
	s_nop 0
	ds_write_b32 v139, v190 offset:448
	ds_write_b32 v139, v196 offset:960
	v_mul_f32_e32 v186, v120, v228
	v_mul_f32_e32 v187, v121, v229
	v_rndne_f32_e32 v186, v186
	v_rndne_f32_e32 v187, v187
	v_cvt_i32_f32_sdwa v190, v186 dst_sel:BYTE_0 dst_unused:UNUSED_PAD src0_sel:DWORD
	v_cvt_i32_f32_sdwa v196, v187 dst_sel:BYTE_0 dst_unused:UNUSED_PAD src0_sel:DWORD
	v_mul_f32_e32 v186, v124, v228
	v_mul_f32_e32 v187, v125, v229
	v_rndne_f32_e32 v186, v186
	v_rndne_f32_e32 v187, v187
	v_cvt_i32_f32_sdwa v190, v186 dst_sel:BYTE_1 dst_unused:UNUSED_PRESERVE src0_sel:DWORD
	v_cvt_i32_f32_sdwa v196, v187 dst_sel:BYTE_1 dst_unused:UNUSED_PRESERVE src0_sel:DWORD
	v_mul_f32_e32 v186, v128, v228
	v_mul_f32_e32 v187, v129, v229
	v_rndne_f32_e32 v186, v186
	v_rndne_f32_e32 v187, v187
	v_cvt_i32_f32_sdwa v190, v186 dst_sel:BYTE_2 dst_unused:UNUSED_PRESERVE src0_sel:DWORD
	v_cvt_i32_f32_sdwa v196, v187 dst_sel:BYTE_2 dst_unused:UNUSED_PRESERVE src0_sel:DWORD
	v_mul_f32_e32 v186, v132, v228
	v_mul_f32_e32 v187, v133, v229
	v_rndne_f32_e32 v186, v186
	v_rndne_f32_e32 v187, v187
	v_cvt_i32_f32_sdwa v190, v186 dst_sel:BYTE_3 dst_unused:UNUSED_PRESERVE src0_sel:DWORD
	v_cvt_i32_f32_sdwa v196, v187 dst_sel:BYTE_3 dst_unused:UNUSED_PRESERVE src0_sel:DWORD
	s_nop 0
	ds_write_b32 v139, v190 offset:1472
	ds_write_b32 v139, v196 offset:1984
	s_cmp_ge_u32 s10, 0x280
	s_cbranch_scc1 .Lc16_mixer_nopf_7
	global_load_dwordx4 v[118:121], v138, s[56:57]
	s_add_u32 s56, s56, 0xa000
	s_addc_u32 s57, s57, 0
	global_load_dwordx4 v[122:125], v138, s[56:57]
	s_add_u32 s56, s56, 0xa000
	s_addc_u32 s57, s57, 0
	global_load_dwordx4 v[126:129], v138, s[56:57]
	s_add_u32 s56, s56, 0xa000
	s_addc_u32 s57, s57, 0
	global_load_dwordx4 v[130:133], v138, s[56:57]

.Lc16p3_ffn2_nocm:
	v_div_scale_f32 v175, s[58:59], v220, v220, s11
	v_rcp_f32_e32 v176, v175
	s_nop 0
	v_fma_f32 v177, -v175, v176, 1.0
	v_fmac_f32_e32 v176, v177, v176
	v_div_scale_f32 v177, vcc, s11, v220, s11
	v_mul_f32_e32 v178, v177, v176
	v_fma_f32 v180, -v175, v178, v177
	v_fmac_f32_e32 v178, v180, v176
	v_fma_f32 v175, -v175, v178, v177
	s_nop 0
	v_div_fmas_f32 v175, v175, v176, v178
	v_div_fixup_f32 v175, v175, v220, s11
	v_cmp_lt_f32_e32 vcc, 0, v220
	s_nop 1
	v_cndmask_b32_e32 v226, 0, v175, vcc
	v_div_scale_f32 v175, s[58:59], v221, v221, s11
	v_rcp_f32_e32 v176, v175
	s_nop 0
	v_fma_f32 v177, -v175, v176, 1.0
	v_fmac_f32_e32 v176, v177, v176
	v_div_scale_f32 v177, vcc, s11, v221, s11
	v_mul_f32_e32 v178, v177, v176
	v_fma_f32 v180, -v175, v178, v177
	v_fmac_f32_e32 v178, v180, v176
	v_fma_f32 v175, -v175, v178, v177
	s_nop 0
	v_div_fmas_f32 v175, v175, v176, v178
	v_div_fixup_f32 v175, v175, v221, s11
	v_cmp_lt_f32_e32 vcc, 0, v221
	s_nop 1
	v_cndmask_b32_e32 v227, 0, v175, vcc
	v_div_scale_f32 v175, s[58:59], v222, v222, s11
	v_rcp_f32_e32 v176, v175
	s_nop 0
	v_fma_f32 v177, -v175, v176, 1.0
	v_fmac_f32_e32 v176, v177, v176
	v_div_scale_f32 v177, vcc, s11, v222, s11
	v_mul_f32_e32 v178, v177, v176
	v_fma_f32 v180, -v175, v178, v177
	v_fmac_f32_e32 v178, v180, v176
	v_fma_f32 v175, -v175, v178, v177
	s_nop 0
	v_div_fmas_f32 v175, v175, v176, v178
	v_div_fixup_f32 v175, v175, v222, s11
	v_cmp_lt_f32_e32 vcc, 0, v222
	s_nop 1
	v_cndmask_b32_e32 v228, 0, v175, vcc
	v_div_scale_f32 v175, s[58:59], v223, v223, s11
	v_rcp_f32_e32 v176, v175
	s_nop 0
	v_fma_f32 v177, -v175, v176, 1.0
	v_fmac_f32_e32 v176, v177, v176
	v_div_scale_f32 v177, vcc, s11, v223, s11
	v_mul_f32_e32 v178, v177, v176
	v_fma_f32 v180, -v175, v178, v177
	v_fmac_f32_e32 v178, v180, v176
	v_fma_f32 v175, -v175, v178, v177
	s_nop 0
	v_div_fmas_f32 v175, v175, v176, v178
	v_div_fixup_f32 v175, v175, v223, s11
	v_cmp_lt_f32_e32 vcc, 0, v223
	s_nop 1
	v_cndmask_b32_e32 v229, 0, v175, vcc
	s_add_u32 s4, s0, s33
	s_lshl_b32 s3, s4, 6
	s_add_u32 s54, s52, s3
	s_addc_u32 s55, s53, 0
	v_mul_f32_e32 v186, v6, v226
	v_mul_f32_e32 v187, v7, v227
	v_rndne_f32_e32 v186, v186
	v_rndne_f32_e32 v187, v187
	v_cvt_i32_f32_sdwa v190, v186 dst_sel:BYTE_0 dst_unused:UNUSED_PAD src0_sel:DWORD
	v_cvt_i32_f32_sdwa v196, v187 dst_sel:BYTE_0 dst_unused:UNUSED_PAD src0_sel:DWORD
	v_mul_f32_e32 v186, v10, v226
	v_mul_f32_e32 v187, v11, v227
	v_rndne_f32_e32 v186, v186
	v_rndne_f32_e32 v187, v187
	v_cvt_i32_f32_sdwa v190, v186 dst_sel:BYTE_1 dst_unused:UNUSED_PRESERVE src0_sel:DWORD
	v_cvt_i32_f32_sdwa v196, v187 dst_sel:BYTE_1 dst_unused:UNUSED_PRESERVE src0_sel:DWORD
	v_mul_f32_e32 v186, v14, v226
	v_mul_f32_e32 v187, v15, v227
	v_rndne_f32_e32 v186, v186
	v_rndne_f32_e32 v187, v187
	v_cvt_i32_f32_sdwa v190, v186 dst_sel:BYTE_2 dst_unused:UNUSED_PRESERVE src0_sel:DWORD
	v_cvt_i32_f32_sdwa v196, v187 dst_sel:BYTE_2 dst_unused:UNUSED_PRESERVE src0_sel:DWORD
	v_mul_f32_e32 v186, v18, v226
	v_mul_f32_e32 v187, v19, v227
	v_rndne_f32_e32 v186, v186
	v_rndne_f32_e32 v187, v187
	v_cvt_i32_f32_sdwa v190, v186 dst_sel:BYTE_3 dst_unused:UNUSED_PRESERVE src0_sel:DWORD
	v_cvt_i32_f32_sdwa v196, v187 dst_sel:BYTE_3 dst_unused:UNUSED_PRESERVE src0_sel:DWORD
	s_nop 0
	ds_write_b32 v139, v190 offset:0
	ds_write_b32 v139, v196 offset:512
	v_mul_f32_e32 v186, v8, v228
	v_mul_f32_e32 v187, v9, v229
	v_rndne_f32_e32 v186, v186
	v_rndne_f32_e32 v187, v187
	v_cvt_i32_f32_sdwa v190, v186 dst_sel:BYTE_0 dst_unused:UNUSED_PAD src0_sel:DWORD
	v_cvt_i32_f32_sdwa v196, v187 dst_sel:BYTE_0 dst_unused:UNUSED_PAD src0_sel:DWORD
	v_mul_f32_e32 v186, v12, v228
	v_mul_f32_e32 v187, v13, v229
	v_rndne_f32_e32 v186, v186
	v_rndne_f32_e32 v187, v187
	v_cvt_i32_f32_sdwa v190, v186 dst_sel:BYTE_1 dst_unused:UNUSED_PRESERVE src0_sel:DWORD
	v_cvt_i32_f32_sdwa v196, v187 dst_sel:BYTE_1 dst_unused:UNUSED_PRESERVE src0_sel:DWORD
	v_mul_f32_e32 v186, v16, v228
	v_mul_f32_e32 v187, v17, v229
	v_rndne_f32_e32 v186, v186
	v_rndne_f32_e32 v187, v187
	v_cvt_i32_f32_sdwa v190, v186 dst_sel:BYTE_2 dst_unused:UNUSED_PRESERVE src0_sel:DWORD
	v_cvt_i32_f32_sdwa v196, v187 dst_sel:BYTE_2 dst_unused:UNUSED_PRESERVE src0_sel:DWORD
	v_mul_f32_e32 v186, v20, v228
	v_mul_f32_e32 v187, v21, v229
	v_rndne_f32_e32 v186, v186
	v_rndne_f32_e32 v187, v187
	v_cvt_i32_f32_sdwa v190, v186 dst_sel:BYTE_3 dst_unused:UNUSED_PRESERVE src0_sel:DWORD
	v_cvt_i32_f32_sdwa v196, v187 dst_sel:BYTE_3 dst_unused:UNUSED_PRESERVE src0_sel:DWORD
	s_nop 0
	ds_write_b32 v139, v190 offset:1024
	ds_write_b32 v139, v196 offset:1536
	s_cmp_ge_u32 s4, 0x560
	s_cbranch_scc1 .Lc16p3_ffn2_nopf_0
	global_load_dwordx4 v[6:9], v138, s[54:55]
	s_add_u32 s54, s54, 0x15800
	s_addc_u32 s55, s55, 0
	global_load_dwordx4 v[10:13], v138, s[54:55]
	s_add_u32 s54, s54, 0x15800
	s_addc_u32 s55, s55, 0
	global_load_dwordx4 v[14:17], v138, s[54:55]
	s_add_u32 s54, s54, 0x15800
	s_addc_u32 s55, s55, 0
	global_load_dwordx4 v[18:21], v138, s[54:55]
	s_add_u32 s54, s54, 0x51f800
	s_addc_u32 s55, s55, 0
.Lc16p3_ffn2_nopf_0:
	v_mul_f32_e32 v186, v22, v226
	v_mul_f32_e32 v187, v23, v227
	v_rndne_f32_e32 v186, v186
	v_rndne_f32_e32 v187, v187
	v_cvt_i32_f32_sdwa v190, v186 dst_sel:BYTE_0 dst_unused:UNUSED_PAD src0_sel:DWORD
	v_cvt_i32_f32_sdwa v196, v187 dst_sel:BYTE_0 dst_unused:UNUSED_PAD src0_sel:DWORD
	v_mul_f32_e32 v186, v26, v226
	v_mul_f32_e32 v187, v27, v227
	v_rndne_f32_e32 v186, v186
	v_rndne_f32_e32 v187, v187
	v_cvt_i32_f32_sdwa v190, v186 dst_sel:BYTE_1 dst_unused:UNUSED_PRESERVE src0_sel:DWORD
	v_cvt_i32_f32_sdwa v196, v187 dst_sel:BYTE_1 dst_unused:UNUSED_PRESERVE src0_sel:DWORD
	v_mul_f32_e32 v186, v30, v226
	v_mul_f32_e32 v187, v31, v227
	v_rndne_f32_e32 v186, v186
	v_rndne_f32_e32 v187, v187
	v_cvt_i32_f32_sdwa v190, v186 dst_sel:BYTE_2 dst_unused:UNUSED_PRESERVE src0_sel:DWORD
	v_cvt_i32_f32_sdwa v196, v187 dst_sel:BYTE_2 dst_unused:UNUSED_PRESERVE src0_sel:DWORD
	v_mul_f32_e32 v186, v34, v226
	v_mul_f32_e32 v187, v35, v227
	v_rndne_f32_e32 v186, v186
	v_rndne_f32_e32 v187, v187
	v_cvt_i32_f32_sdwa v190, v186 dst_sel:BYTE_3 dst_unused:UNUSED_PRESERVE src0_sel:DWORD
	v_cvt_i32_f32_sdwa v196, v187 dst_sel:BYTE_3 dst_unused:UNUSED_PRESERVE src0_sel:DWORD
	s_nop 0
	ds_write_b32 v139, v190 offset:64
	ds_write_b32 v139, v196 offset:576
	v_mul_f32_e32 v186, v24, v228
	v_mul_f32_e32 v187, v25, v229
	v_rndne_f32_e32 v186, v186
	v_rndne_f32_e32 v187, v187
	v_cvt_i32_f32_sdwa v190, v186 dst_sel:BYTE_0 dst_unused:UNUSED_PAD src0_sel:DWORD
	v_cvt_i32_f32_sdwa v196, v187 dst_sel:BYTE_0 dst_unused:UNUSED_PAD src0_sel:DWORD
	v_mul_f32_e32 v186, v28, v228
	v_mul_f32_e32 v187, v29, v229
	v_rndne_f32_e32 v186, v186
	v_rndne_f32_e32 v187, v187
	v_cvt_i32_f32_sdwa v190, v186 dst_sel:BYTE_1 dst_unused:UNUSED_PRESERVE src0_sel:DWORD
	v_cvt_i32_f32_sdwa v196, v187 dst_sel:BYTE_1 dst_unused:UNUSED_PRESERVE src0_sel:DWORD
	v_mul_f32_e32 v186, v32, v228
	v_mul_f32_e32 v187, v33, v229
	v_rndne_f32_e32 v186, v186
	v_rndne_f32_e32 v187, v187
	v_cvt_i32_f32_sdwa v190, v186 dst_sel:BYTE_2 dst_unused:UNUSED_PRESERVE src0_sel:DWORD
	v_cvt_i32_f32_sdwa v196, v187 dst_sel:BYTE_2 dst_unused:UNUSED_PRESERVE src0_sel:DWORD
	v_mul_f32_e32 v186, v36, v228
	v_mul_f32_e32 v187, v37, v229
	v_rndne_f32_e32 v186, v186
	v_rndne_f32_e32 v187, v187
	v_cvt_i32_f32_sdwa v190, v186 dst_sel:BYTE_3 dst_unused:UNUSED_PRESERVE src0_sel:DWORD
	v_cvt_i32_f32_sdwa v196, v187 dst_sel:BYTE_3 dst_unused:UNUSED_PRESERVE src0_sel:DWORD
	s_nop 0
	ds_write_b32 v139, v190 offset:1088
	ds_write_b32 v139, v196 offset:1600
	s_cmp_ge_u32 s4, 0x560
	s_cbranch_scc1 .Lc16p3_ffn2_nopf_1
	global_load_dwordx4 v[22:25], v138, s[54:55]
	s_add_u32 s54, s54, 0x15800
	s_addc_u32 s55, s55, 0
	global_load_dwordx4 v[26:29], v138, s[54:55]
	s_add_u32 s54, s54, 0x15800
	s_addc_u32 s55, s55, 0
	global_load_dwordx4 v[30:33], v138, s[54:55]
	s_add_u32 s54, s54, 0x15800
	s_addc_u32 s55, s55, 0
	global_load_dwordx4 v[34:37], v138, s[54:55]
	s_add_u32 s54, s54, 0x51f800
	s_addc_u32 s55, s55, 0
.Lc16p3_ffn2_nopf_1:
	v_mul_f32_e32 v186, v38, v226
	v_mul_f32_e32 v187, v39, v227
	v_rndne_f32_e32 v186, v186
	v_rndne_f32_e32 v187, v187
	v_cvt_i32_f32_sdwa v190, v186 dst_sel:BYTE_0 dst_unused:UNUSED_PAD src0_sel:DWORD
	v_cvt_i32_f32_sdwa v196, v187 dst_sel:BYTE_0 dst_unused:UNUSED_PAD src0_sel:DWORD
	v_mul_f32_e32 v186, v42, v226
	v_mul_f32_e32 v187, v43, v227
	v_rndne_f32_e32 v186, v186
	v_rndne_f32_e32 v187, v187
	v_cvt_i32_f32_sdwa v190, v186 dst_sel:BYTE_1 dst_unused:UNUSED_PRESERVE src0_sel:DWORD
	v_cvt_i32_f32_sdwa v196, v187 dst_sel:BYTE_1 dst_unused:UNUSED_PRESERVE src0_sel:DWORD
	v_mul_f32_e32 v186, v46, v226
	v_mul_f32_e32 v187, v47, v227
	v_rndne_f32_e32 v186, v186
	v_rndne_f32_e32 v187, v187
	v_cvt_i32_f32_sdwa v190, v186 dst_sel:BYTE_2 dst_unused:UNUSED_PRESERVE src0_sel:DWORD
	v_cvt_i32_f32_sdwa v196, v187 dst_sel:BYTE_2 dst_unused:UNUSED_PRESERVE src0_sel:DWORD
	v_mul_f32_e32 v186, v50, v226
	v_mul_f32_e32 v187, v51, v227
	v_rndne_f32_e32 v186, v186
	v_rndne_f32_e32 v187, v187
	v_cvt_i32_f32_sdwa v190, v186 dst_sel:BYTE_3 dst_unused:UNUSED_PRESERVE src0_sel:DWORD
	v_cvt_i32_f32_sdwa v196, v187 dst_sel:BYTE_3 dst_unused:UNUSED_PRESERVE src0_sel:DWORD
	s_nop 0
	ds_write_b32 v139, v190 offset:128
	ds_write_b32 v139, v196 offset:640
	v_mul_f32_e32 v186, v40, v228
	v_mul_f32_e32 v187, v41, v229
	v_rndne_f32_e32 v186, v186
	v_rndne_f32_e32 v187, v187
	v_cvt_i32_f32_sdwa v190, v186 dst_sel:BYTE_0 dst_unused:UNUSED_PAD src0_sel:DWORD
	v_cvt_i32_f32_sdwa v196, v187 dst_sel:BYTE_0 dst_unused:UNUSED_PAD src0_sel:DWORD
	v_mul_f32_e32 v186, v44, v228
	v_mul_f32_e32 v187, v45, v229
	v_rndne_f32_e32 v186, v186
	v_rndne_f32_e32 v187, v187
	v_cvt_i32_f32_sdwa v190, v186 dst_sel:BYTE_1 dst_unused:UNUSED_PRESERVE src0_sel:DWORD
	v_cvt_i32_f32_sdwa v196, v187 dst_sel:BYTE_1 dst_unused:UNUSED_PRESERVE src0_sel:DWORD
	v_mul_f32_e32 v186, v48, v228
	v_mul_f32_e32 v187, v49, v229
	v_rndne_f32_e32 v186, v186
	v_rndne_f32_e32 v187, v187
	v_cvt_i32_f32_sdwa v190, v186 dst_sel:BYTE_2 dst_unused:UNUSED_PRESERVE src0_sel:DWORD
	v_cvt_i32_f32_sdwa v196, v187 dst_sel:BYTE_2 dst_unused:UNUSED_PRESERVE src0_sel:DWORD
	v_mul_f32_e32 v186, v52, v228
	v_mul_f32_e32 v187, v53, v229
	v_rndne_f32_e32 v186, v186
	v_rndne_f32_e32 v187, v187
	v_cvt_i32_f32_sdwa v190, v186 dst_sel:BYTE_3 dst_unused:UNUSED_PRESERVE src0_sel:DWORD
	v_cvt_i32_f32_sdwa v196, v187 dst_sel:BYTE_3 dst_unused:UNUSED_PRESERVE src0_sel:DWORD
	s_nop 0
	ds_write_b32 v139, v190 offset:1152
	ds_write_b32 v139, v196 offset:1664
	s_cmp_ge_u32 s4, 0x560
	s_cbranch_scc1 .Lc16p3_ffn2_nopf_2
	global_load_dwordx4 v[38:41], v138, s[54:55]
	s_add_u32 s54, s54, 0x15800
	s_addc_u32 s55, s55, 0
	global_load_dwordx4 v[42:45], v138, s[54:55]
	s_add_u32 s54, s54, 0x15800
	s_addc_u32 s55, s55, 0
	global_load_dwordx4 v[46:49], v138, s[54:55]
	s_add_u32 s54, s54, 0x15800
	s_addc_u32 s55, s55, 0
	global_load_dwordx4 v[50:53], v138, s[54:55]
	s_add_u32 s54, s54, 0x51f800
	s_addc_u32 s55, s55, 0
.Lc16p3_ffn2_nopf_2:
	v_mul_f32_e32 v186, v54, v226
	v_mul_f32_e32 v187, v55, v227
	v_rndne_f32_e32 v186, v186
	v_rndne_f32_e32 v187, v187
	v_cvt_i32_f32_sdwa v190, v186 dst_sel:BYTE_0 dst_unused:UNUSED_PAD src0_sel:DWORD
	v_cvt_i32_f32_sdwa v196, v187 dst_sel:BYTE_0 dst_unused:UNUSED_PAD src0_sel:DWORD
	v_mul_f32_e32 v186, v58, v226
	v_mul_f32_e32 v187, v59, v227
	v_rndne_f32_e32 v186, v186
	v_rndne_f32_e32 v187, v187
	v_cvt_i32_f32_sdwa v190, v186 dst_sel:BYTE_1 dst_unused:UNUSED_PRESERVE src0_sel:DWORD
	v_cvt_i32_f32_sdwa v196, v187 dst_sel:BYTE_1 dst_unused:UNUSED_PRESERVE src0_sel:DWORD
	v_mul_f32_e32 v186, v62, v226
	v_mul_f32_e32 v187, v63, v227
	v_rndne_f32_e32 v186, v186
	v_rndne_f32_e32 v187, v187
	v_cvt_i32_f32_sdwa v190, v186 dst_sel:BYTE_2 dst_unused:UNUSED_PRESERVE src0_sel:DWORD
	v_cvt_i32_f32_sdwa v196, v187 dst_sel:BYTE_2 dst_unused:UNUSED_PRESERVE src0_sel:DWORD
	v_mul_f32_e32 v186, v66, v226
	v_mul_f32_e32 v187, v67, v227
	v_rndne_f32_e32 v186, v186
	v_rndne_f32_e32 v187, v187
	v_cvt_i32_f32_sdwa v190, v186 dst_sel:BYTE_3 dst_unused:UNUSED_PRESERVE src0_sel:DWORD
	v_cvt_i32_f32_sdwa v196, v187 dst_sel:BYTE_3 dst_unused:UNUSED_PRESERVE src0_sel:DWORD
	s_nop 0
	ds_write_b32 v139, v190 offset:192
	ds_write_b32 v139, v196 offset:704
	v_mul_f32_e32 v186, v56, v228
	v_mul_f32_e32 v187, v57, v229
	v_rndne_f32_e32 v186, v186
	v_rndne_f32_e32 v187, v187
	v_cvt_i32_f32_sdwa v190, v186 dst_sel:BYTE_0 dst_unused:UNUSED_PAD src0_sel:DWORD
	v_cvt_i32_f32_sdwa v196, v187 dst_sel:BYTE_0 dst_unused:UNUSED_PAD src0_sel:DWORD
	v_mul_f32_e32 v186, v60, v228
	v_mul_f32_e32 v187, v61, v229
	v_rndne_f32_e32 v186, v186
	v_rndne_f32_e32 v187, v187
	v_cvt_i32_f32_sdwa v190, v186 dst_sel:BYTE_1 dst_unused:UNUSED_PRESERVE src0_sel:DWORD
	v_cvt_i32_f32_sdwa v196, v187 dst_sel:BYTE_1 dst_unused:UNUSED_PRESERVE src0_sel:DWORD
	v_mul_f32_e32 v186, v64, v228
	v_mul_f32_e32 v187, v65, v229
	v_rndne_f32_e32 v186, v186
	v_rndne_f32_e32 v187, v187
	v_cvt_i32_f32_sdwa v190, v186 dst_sel:BYTE_2 dst_unused:UNUSED_PRESERVE src0_sel:DWORD
	v_cvt_i32_f32_sdwa v196, v187 dst_sel:BYTE_2 dst_unused:UNUSED_PRESERVE src0_sel:DWORD
	v_mul_f32_e32 v186, v68, v228
	v_mul_f32_e32 v187, v69, v229
	v_rndne_f32_e32 v186, v186
	v_rndne_f32_e32 v187, v187
	v_cvt_i32_f32_sdwa v190, v186 dst_sel:BYTE_3 dst_unused:UNUSED_PRESERVE src0_sel:DWORD
	v_cvt_i32_f32_sdwa v196, v187 dst_sel:BYTE_3 dst_unused:UNUSED_PRESERVE src0_sel:DWORD
	s_nop 0
	ds_write_b32 v139, v190 offset:1216
	ds_write_b32 v139, v196 offset:1728
	s_cmp_ge_u32 s4, 0x560
	s_cbranch_scc1 .Lc16p3_ffn2_nopf_3
	global_load_dwordx4 v[54:57], v138, s[54:55]
	s_add_u32 s54, s54, 0x15800
	s_addc_u32 s55, s55, 0
	global_load_dwordx4 v[58:61], v138, s[54:55]
	s_add_u32 s54, s54, 0x15800
	s_addc_u32 s55, s55, 0
	global_load_dwordx4 v[62:65], v138, s[54:55]
	s_add_u32 s54, s54, 0x15800
	s_addc_u32 s55, s55, 0
	global_load_dwordx4 v[66:69], v138, s[54:55]
	s_add_u32 s54, s54, 0x51f800
	s_addc_u32 s55, s55, 0
.Lc16p3_ffn2_nopf_3:
	v_mul_f32_e32 v186, v70, v226
	v_mul_f32_e32 v187, v71, v227
	v_rndne_f32_e32 v186, v186
	v_rndne_f32_e32 v187, v187
	v_cvt_i32_f32_sdwa v190, v186 dst_sel:BYTE_0 dst_unused:UNUSED_PAD src0_sel:DWORD
	v_cvt_i32_f32_sdwa v196, v187 dst_sel:BYTE_0 dst_unused:UNUSED_PAD src0_sel:DWORD
	v_mul_f32_e32 v186, v74, v226
	v_mul_f32_e32 v187, v75, v227
	v_rndne_f32_e32 v186, v186
	v_rndne_f32_e32 v187, v187
	v_cvt_i32_f32_sdwa v190, v186 dst_sel:BYTE_1 dst_unused:UNUSED_PRESERVE src0_sel:DWORD
	v_cvt_i32_f32_sdwa v196, v187 dst_sel:BYTE_1 dst_unused:UNUSED_PRESERVE src0_sel:DWORD
	v_mul_f32_e32 v186, v78, v226
	v_mul_f32_e32 v187, v79, v227
	v_rndne_f32_e32 v186, v186
	v_rndne_f32_e32 v187, v187
	v_cvt_i32_f32_sdwa v190, v186 dst_sel:BYTE_2 dst_unused:UNUSED_PRESERVE src0_sel:DWORD
	v_cvt_i32_f32_sdwa v196, v187 dst_sel:BYTE_2 dst_unused:UNUSED_PRESERVE src0_sel:DWORD
	v_mul_f32_e32 v186, v82, v226
	v_mul_f32_e32 v187, v83, v227
	v_rndne_f32_e32 v186, v186
	v_rndne_f32_e32 v187, v187
	v_cvt_i32_f32_sdwa v190, v186 dst_sel:BYTE_3 dst_unused:UNUSED_PRESERVE src0_sel:DWORD
	v_cvt_i32_f32_sdwa v196, v187 dst_sel:BYTE_3 dst_unused:UNUSED_PRESERVE src0_sel:DWORD
	s_nop 0
	ds_write_b32 v139, v190 offset:256
	ds_write_b32 v139, v196 offset:768
	v_mul_f32_e32 v186, v72, v228
	v_mul_f32_e32 v187, v73, v229
	v_rndne_f32_e32 v186, v186
	v_rndne_f32_e32 v187, v187
	v_cvt_i32_f32_sdwa v190, v186 dst_sel:BYTE_0 dst_unused:UNUSED_PAD src0_sel:DWORD
	v_cvt_i32_f32_sdwa v196, v187 dst_sel:BYTE_0 dst_unused:UNUSED_PAD src0_sel:DWORD
	v_mul_f32_e32 v186, v76, v228
	v_mul_f32_e32 v187, v77, v229
	v_rndne_f32_e32 v186, v186
	v_rndne_f32_e32 v187, v187
	v_cvt_i32_f32_sdwa v190, v186 dst_sel:BYTE_1 dst_unused:UNUSED_PRESERVE src0_sel:DWORD
	v_cvt_i32_f32_sdwa v196, v187 dst_sel:BYTE_1 dst_unused:UNUSED_PRESERVE src0_sel:DWORD
	v_mul_f32_e32 v186, v80, v228
	v_mul_f32_e32 v187, v81, v229
	v_rndne_f32_e32 v186, v186
	v_rndne_f32_e32 v187, v187
	v_cvt_i32_f32_sdwa v190, v186 dst_sel:BYTE_2 dst_unused:UNUSED_PRESERVE src0_sel:DWORD
	v_cvt_i32_f32_sdwa v196, v187 dst_sel:BYTE_2 dst_unused:UNUSED_PRESERVE src0_sel:DWORD
	v_mul_f32_e32 v186, v84, v228
	v_mul_f32_e32 v187, v85, v229
	v_rndne_f32_e32 v186, v186
	v_rndne_f32_e32 v187, v187
	v_cvt_i32_f32_sdwa v190, v186 dst_sel:BYTE_3 dst_unused:UNUSED_PRESERVE src0_sel:DWORD
	v_cvt_i32_f32_sdwa v196, v187 dst_sel:BYTE_3 dst_unused:UNUSED_PRESERVE src0_sel:DWORD
	s_nop 0
	ds_write_b32 v139, v190 offset:1280
	ds_write_b32 v139, v196 offset:1792
	s_cmp_ge_u32 s4, 0x560
	s_cbranch_scc1 .Lc16p3_ffn2_nopf_4
	global_load_dwordx4 v[70:73], v138, s[54:55]
	s_add_u32 s54, s54, 0x15800
	s_addc_u32 s55, s55, 0
	global_load_dwordx4 v[74:77], v138, s[54:55]
	s_add_u32 s54, s54, 0x15800
	s_addc_u32 s55, s55, 0
	global_load_dwordx4 v[78:81], v138, s[54:55]
	s_add_u32 s54, s54, 0x15800
	s_addc_u32 s55, s55, 0
	global_load_dwordx4 v[82:85], v138, s[54:55]
	s_add_u32 s54, s54, 0x51f800
	s_addc_u32 s55, s55, 0
.Lc16p3_ffn2_nopf_4:
	v_mul_f32_e32 v186, v86, v226
	v_mul_f32_e32 v187, v87, v227
	v_rndne_f32_e32 v186, v186
	v_rndne_f32_e32 v187, v187
	v_cvt_i32_f32_sdwa v190, v186 dst_sel:BYTE_0 dst_unused:UNUSED_PAD src0_sel:DWORD
	v_cvt_i32_f32_sdwa v196, v187 dst_sel:BYTE_0 dst_unused:UNUSED_PAD src0_sel:DWORD
	v_mul_f32_e32 v186, v90, v226
	v_mul_f32_e32 v187, v91, v227
	v_rndne_f32_e32 v186, v186
	v_rndne_f32_e32 v187, v187
	v_cvt_i32_f32_sdwa v190, v186 dst_sel:BYTE_1 dst_unused:UNUSED_PRESERVE src0_sel:DWORD
	v_cvt_i32_f32_sdwa v196, v187 dst_sel:BYTE_1 dst_unused:UNUSED_PRESERVE src0_sel:DWORD
	v_mul_f32_e32 v186, v94, v226
	v_mul_f32_e32 v187, v95, v227
	v_rndne_f32_e32 v186, v186
	v_rndne_f32_e32 v187, v187
	v_cvt_i32_f32_sdwa v190, v186 dst_sel:BYTE_2 dst_unused:UNUSED_PRESERVE src0_sel:DWORD
	v_cvt_i32_f32_sdwa v196, v187 dst_sel:BYTE_2 dst_unused:UNUSED_PRESERVE src0_sel:DWORD
	v_mul_f32_e32 v186, v98, v226
	v_mul_f32_e32 v187, v99, v227
	v_rndne_f32_e32 v186, v186
	v_rndne_f32_e32 v187, v187
	v_cvt_i32_f32_sdwa v190, v186 dst_sel:BYTE_3 dst_unused:UNUSED_PRESERVE src0_sel:DWORD
	v_cvt_i32_f32_sdwa v196, v187 dst_sel:BYTE_3 dst_unused:UNUSED_PRESERVE src0_sel:DWORD
	s_nop 0
	ds_write_b32 v139, v190 offset:320
	ds_write_b32 v139, v196 offset:832
	v_mul_f32_e32 v186, v88, v228
	v_mul_f32_e32 v187, v89, v229
	v_rndne_f32_e32 v186, v186
	v_rndne_f32_e32 v187, v187
	v_cvt_i32_f32_sdwa v190, v186 dst_sel:BYTE_0 dst_unused:UNUSED_PAD src0_sel:DWORD
	v_cvt_i32_f32_sdwa v196, v187 dst_sel:BYTE_0 dst_unused:UNUSED_PAD src0_sel:DWORD
	v_mul_f32_e32 v186, v92, v228
	v_mul_f32_e32 v187, v93, v229
	v_rndne_f32_e32 v186, v186
	v_rndne_f32_e32 v187, v187
	v_cvt_i32_f32_sdwa v190, v186 dst_sel:BYTE_1 dst_unused:UNUSED_PRESERVE src0_sel:DWORD
	v_cvt_i32_f32_sdwa v196, v187 dst_sel:BYTE_1 dst_unused:UNUSED_PRESERVE src0_sel:DWORD
	v_mul_f32_e32 v186, v96, v228
	v_mul_f32_e32 v187, v97, v229
	v_rndne_f32_e32 v186, v186
	v_rndne_f32_e32 v187, v187
	v_cvt_i32_f32_sdwa v190, v186 dst_sel:BYTE_2 dst_unused:UNUSED_PRESERVE src0_sel:DWORD
	v_cvt_i32_f32_sdwa v196, v187 dst_sel:BYTE_2 dst_unused:UNUSED_PRESERVE src0_sel:DWORD
	v_mul_f32_e32 v186, v100, v228
	v_mul_f32_e32 v187, v101, v229
	v_rndne_f32_e32 v186, v186
	v_rndne_f32_e32 v187, v187
	v_cvt_i32_f32_sdwa v190, v186 dst_sel:BYTE_3 dst_unused:UNUSED_PRESERVE src0_sel:DWORD
	v_cvt_i32_f32_sdwa v196, v187 dst_sel:BYTE_3 dst_unused:UNUSED_PRESERVE src0_sel:DWORD
	s_nop 0
	ds_write_b32 v139, v190 offset:1344
	ds_write_b32 v139, v196 offset:1856
	s_cmp_ge_u32 s4, 0x560
	s_cbranch_scc1 .Lc16p3_ffn2_nopf_5
	global_load_dwordx4 v[86:89], v138, s[54:55]
	s_add_u32 s54, s54, 0x15800
	s_addc_u32 s55, s55, 0
	global_load_dwordx4 v[90:93], v138, s[54:55]
	s_add_u32 s54, s54, 0x15800
	s_addc_u32 s55, s55, 0
	global_load_dwordx4 v[94:97], v138, s[54:55]
	s_add_u32 s54, s54, 0x15800
	s_addc_u32 s55, s55, 0
	global_load_dwordx4 v[98:101], v138, s[54:55]
	s_add_u32 s54, s54, 0x51f800
	s_addc_u32 s55, s55, 0
.Lc16p3_ffn2_nopf_5:
	v_mul_f32_e32 v186, v102, v226
	v_mul_f32_e32 v187, v103, v227
	v_rndne_f32_e32 v186, v186
	v_rndne_f32_e32 v187, v187
	v_cvt_i32_f32_sdwa v190, v186 dst_sel:BYTE_0 dst_unused:UNUSED_PAD src0_sel:DWORD
	v_cvt_i32_f32_sdwa v196, v187 dst_sel:BYTE_0 dst_unused:UNUSED_PAD src0_sel:DWORD
	v_mul_f32_e32 v186, v106, v226
	v_mul_f32_e32 v187, v107, v227
	v_rndne_f32_e32 v186, v186
	v_rndne_f32_e32 v187, v187
	v_cvt_i32_f32_sdwa v190, v186 dst_sel:BYTE_1 dst_unused:UNUSED_PRESERVE src0_sel:DWORD
	v_cvt_i32_f32_sdwa v196, v187 dst_sel:BYTE_1 dst_unused:UNUSED_PRESERVE src0_sel:DWORD
	v_mul_f32_e32 v186, v110, v226
	v_mul_f32_e32 v187, v111, v227
	v_rndne_f32_e32 v186, v186
	v_rndne_f32_e32 v187, v187
	v_cvt_i32_f32_sdwa v190, v186 dst_sel:BYTE_2 dst_unused:UNUSED_PRESERVE src0_sel:DWORD
	v_cvt_i32_f32_sdwa v196, v187 dst_sel:BYTE_2 dst_unused:UNUSED_PRESERVE src0_sel:DWORD
	v_mul_f32_e32 v186, v114, v226
	v_mul_f32_e32 v187, v115, v227
	v_rndne_f32_e32 v186, v186
	v_rndne_f32_e32 v187, v187
	v_cvt_i32_f32_sdwa v190, v186 dst_sel:BYTE_3 dst_unused:UNUSED_PRESERVE src0_sel:DWORD
	v_cvt_i32_f32_sdwa v196, v187 dst_sel:BYTE_3 dst_unused:UNUSED_PRESERVE src0_sel:DWORD
	s_nop 0
	ds_write_b32 v139, v190 offset:384
	ds_write_b32 v139, v196 offset:896
	v_mul_f32_e32 v186, v104, v228
	v_mul_f32_e32 v187, v105, v229
	v_rndne_f32_e32 v186, v186
	v_rndne_f32_e32 v187, v187
	v_cvt_i32_f32_sdwa v190, v186 dst_sel:BYTE_0 dst_unused:UNUSED_PAD src0_sel:DWORD
	v_cvt_i32_f32_sdwa v196, v187 dst_sel:BYTE_0 dst_unused:UNUSED_PAD src0_sel:DWORD
	v_mul_f32_e32 v186, v108, v228
	v_mul_f32_e32 v187, v109, v229
	v_rndne_f32_e32 v186, v186
	v_rndne_f32_e32 v187, v187
	v_cvt_i32_f32_sdwa v190, v186 dst_sel:BYTE_1 dst_unused:UNUSED_PRESERVE src0_sel:DWORD
	v_cvt_i32_f32_sdwa v196, v187 dst_sel:BYTE_1 dst_unused:UNUSED_PRESERVE src0_sel:DWORD
	v_mul_f32_e32 v186, v112, v228
	v_mul_f32_e32 v187, v113, v229
	v_rndne_f32_e32 v186, v186
	v_rndne_f32_e32 v187, v187
	v_cvt_i32_f32_sdwa v190, v186 dst_sel:BYTE_2 dst_unused:UNUSED_PRESERVE src0_sel:DWORD
	v_cvt_i32_f32_sdwa v196, v187 dst_sel:BYTE_2 dst_unused:UNUSED_PRESERVE src0_sel:DWORD
	v_mul_f32_e32 v186, v116, v228
	v_mul_f32_e32 v187, v117, v229
	v_rndne_f32_e32 v186, v186
	v_rndne_f32_e32 v187, v187
	v_cvt_i32_f32_sdwa v190, v186 dst_sel:BYTE_3 dst_unused:UNUSED_PRESERVE src0_sel:DWORD
	v_cvt_i32_f32_sdwa v196, v187 dst_sel:BYTE_3 dst_unused:UNUSED_PRESERVE src0_sel:DWORD
	s_nop 0
	ds_write_b32 v139, v190 offset:1408
	ds_write_b32 v139, v196 offset:1920
	s_cmp_ge_u32 s4, 0x560
	s_cbranch_scc1 .Lc16p3_ffn2_nopf_6
	global_load_dwordx4 v[102:105], v138, s[54:55]
	s_add_u32 s54, s54, 0x15800
	s_addc_u32 s55, s55, 0
	global_load_dwordx4 v[106:109], v138, s[54:55]
	s_add_u32 s54, s54, 0x15800
	s_addc_u32 s55, s55, 0
	global_load_dwordx4 v[110:113], v138, s[54:55]
	s_add_u32 s54, s54, 0x15800
	s_addc_u32 s55, s55, 0
	global_load_dwordx4 v[114:117], v138, s[54:55]
	s_add_u32 s54, s54, 0x51f800
	s_addc_u32 s55, s55, 0
.Lc16p3_ffn2_nopf_6:
	v_mul_f32_e32 v186, v118, v226
	v_mul_f32_e32 v187, v119, v227
	v_rndne_f32_e32 v186, v186
	v_rndne_f32_e32 v187, v187
	v_cvt_i32_f32_sdwa v190, v186 dst_sel:BYTE_0 dst_unused:UNUSED_PAD src0_sel:DWORD
	v_cvt_i32_f32_sdwa v196, v187 dst_sel:BYTE_0 dst_unused:UNUSED_PAD src0_sel:DWORD
	v_mul_f32_e32 v186, v122, v226
	v_mul_f32_e32 v187, v123, v227
	v_rndne_f32_e32 v186, v186
	v_rndne_f32_e32 v187, v187
	v_cvt_i32_f32_sdwa v190, v186 dst_sel:BYTE_1 dst_unused:UNUSED_PRESERVE src0_sel:DWORD
	v_cvt_i32_f32_sdwa v196, v187 dst_sel:BYTE_1 dst_unused:UNUSED_PRESERVE src0_sel:DWORD
	v_mul_f32_e32 v186, v126, v226
	v_mul_f32_e32 v187, v127, v227
	v_rndne_f32_e32 v186, v186
	v_rndne_f32_e32 v187, v187
	v_cvt_i32_f32_sdwa v190, v186 dst_sel:BYTE_2 dst_unused:UNUSED_PRESERVE src0_sel:DWORD
	v_cvt_i32_f32_sdwa v196, v187 dst_sel:BYTE_2 dst_unused:UNUSED_PRESERVE src0_sel:DWORD
	v_mul_f32_e32 v186, v130, v226
	v_mul_f32_e32 v187, v131, v227
	v_rndne_f32_e32 v186, v186
	v_rndne_f32_e32 v187, v187
	v_cvt_i32_f32_sdwa v190, v186 dst_sel:BYTE_3 dst_unused:UNUSED_PRESERVE src0_sel:DWORD
	v_cvt_i32_f32_sdwa v196, v187 dst_sel:BYTE_3 dst_unused:UNUSED_PRESERVE src0_sel:DWORD
	s_nop 0
	ds_write_b32 v139, v190 offset:448
	ds_write_b32 v139, v196 offset:960
	v_mul_f32_e32 v186, v120, v228
	v_mul_f32_e32 v187, v121, v229
	v_rndne_f32_e32 v186, v186
	v_rndne_f32_e32 v187, v187
	v_cvt_i32_f32_sdwa v190, v186 dst_sel:BYTE_0 dst_unused:UNUSED_PAD src0_sel:DWORD
	v_cvt_i32_f32_sdwa v196, v187 dst_sel:BYTE_0 dst_unused:UNUSED_PAD src0_sel:DWORD
	v_mul_f32_e32 v186, v124, v228
	v_mul_f32_e32 v187, v125, v229
	v_rndne_f32_e32 v186, v186
	v_rndne_f32_e32 v187, v187
	v_cvt_i32_f32_sdwa v190, v186 dst_sel:BYTE_1 dst_unused:UNUSED_PRESERVE src0_sel:DWORD
	v_cvt_i32_f32_sdwa v196, v187 dst_sel:BYTE_1 dst_unused:UNUSED_PRESERVE src0_sel:DWORD
	v_mul_f32_e32 v186, v128, v228
	v_mul_f32_e32 v187, v129, v229
	v_rndne_f32_e32 v186, v186
	v_rndne_f32_e32 v187, v187
	v_cvt_i32_f32_sdwa v190, v186 dst_sel:BYTE_2 dst_unused:UNUSED_PRESERVE src0_sel:DWORD
	v_cvt_i32_f32_sdwa v196, v187 dst_sel:BYTE_2 dst_unused:UNUSED_PRESERVE src0_sel:DWORD
	v_mul_f32_e32 v186, v132, v228
	v_mul_f32_e32 v187, v133, v229
	v_rndne_f32_e32 v186, v186
	v_rndne_f32_e32 v187, v187
	v_cvt_i32_f32_sdwa v190, v186 dst_sel:BYTE_3 dst_unused:UNUSED_PRESERVE src0_sel:DWORD
	v_cvt_i32_f32_sdwa v196, v187 dst_sel:BYTE_3 dst_unused:UNUSED_PRESERVE src0_sel:DWORD
	s_nop 0
	ds_write_b32 v139, v190 offset:1472
	ds_write_b32 v139, v196 offset:1984
	s_cmp_ge_u32 s4, 0x560
	s_cbranch_scc1 .Lc16p3_ffn2_nopf_7
	global_load_dwordx4 v[118:121], v138, s[54:55]
	s_add_u32 s54, s54, 0x15800
	s_addc_u32 s55, s55, 0
	global_load_dwordx4 v[122:125], v138, s[54:55]
	s_add_u32 s54, s54, 0x15800
	s_addc_u32 s55, s55, 0
	global_load_dwordx4 v[126:129], v138, s[54:55]
	s_add_u32 s54, s54, 0x15800
	s_addc_u32 s55, s55, 0
	global_load_dwordx4 v[130:133], v138, s[54:55]
